# dead scalar code removed: 196 unused kernarg pointer loads and their address math in the per-phase prologues
# speedup vs baseline: 1.0125x; 1.0029x over previous
; __global__ void __launch_bounds__(NTHR, 2) hybrid_fwd(Args args) {
;     ...
;     DECL_PTRS
.LBB0_14:
	s_load_dwordx4 s[16:19], s[0:1], 0xa0
	s_mov_b32 s44, s20
	s_mov_b32 s60, s2
	s_mov_b32 s4, 0
	s_lshr_b32 s74, s72, 6
	s_waitcnt lgkmcnt(0)
	s_mov_b64 s[24:25], s[18:19]
	s_lshl_b32 s3, s60, 3
	s_ashr_i32 s5, s4, 31
	s_add_i32 s26, s3, s74
	s_lshl_b32 s28, s44, 3
	s_lshl_b64 s[4:5], s[4:5], 3
	s_add_u32 s4, s0, s4
	s_addc_u32 s5, s1, s5
	s_load_dwordx2 s[8:9], s[4:5], 0x0
	s_mov_b32 s4, 1
	s_waitcnt lgkmcnt(0)
	s_ashr_i32 s5, s4, 31
	s_lshl_b64 s[4:5], s[4:5], 3
	s_add_u32 s4, s0, s4
	s_addc_u32 s5, s1, s5
	s_load_dwordx2 s[30:31], s[4:5], 0x0
	s_mov_b32 s4, 2
	s_waitcnt lgkmcnt(0)
	s_ashr_i32 s5, s4, 31
	s_lshl_b64 s[4:5], s[4:5], 3
	s_add_u32 s4, s0, s4
	s_addc_u32 s5, s1, s5
	s_load_dwordx2 s[6:7], s[4:5], 0x0
	s_mov_b32 s4, 3
	s_waitcnt lgkmcnt(0)
	s_ashr_i32 s5, s4, 31
	s_lshl_b64 s[4:5], s[4:5], 3
	s_add_u32 s4, s0, s4
	s_addc_u32 s5, s1, s5
	s_load_dwordx2 s[10:11], s[4:5], 0x0
	s_mov_b32 s4, 4
	s_waitcnt lgkmcnt(0)
	s_ashr_i32 s5, s4, 31
	s_lshl_b64 s[4:5], s[4:5], 3
	s_add_u32 s4, s0, s4
	s_addc_u32 s5, s1, s5
	s_load_dwordx2 s[14:15], s[4:5], 0x0
	s_waitcnt lgkmcnt(0)
	s_mov_b32 s12, 6
	s_waitcnt lgkmcnt(0)
	s_ashr_i32 s13, s12, 31
	s_lshl_b64 s[4:5], s[12:13], 3
	s_add_u32 s4, s0, s4
	s_addc_u32 s5, s1, s5
	s_load_dwordx2 s[12:13], s[4:5], 0x0
	s_mov_b32 s4, 7
	s_waitcnt lgkmcnt(0)
	s_ashr_i32 s5, s4, 31
	s_lshl_b64 s[4:5], s[4:5], 3
	s_add_u32 s4, s0, s4
	s_addc_u32 s5, s1, s5
	s_load_dwordx2 s[34:35], s[4:5], 0x0
	s_mov_b32 s4, 8
	s_waitcnt lgkmcnt(0)
	s_ashr_i32 s5, s4, 31
	s_lshl_b64 s[4:5], s[4:5], 3
	s_add_u32 s4, s0, s4
	s_addc_u32 s5, s1, s5
	s_load_dwordx2 s[36:37], s[4:5], 0x0
	s_mov_b32 s4, 9
	s_waitcnt lgkmcnt(0)
	s_ashr_i32 s5, s4, 31
	s_lshl_b64 s[4:5], s[4:5], 3
	s_add_u32 s4, s0, s4
	s_addc_u32 s5, s1, s5
	s_load_dwordx2 s[52:53], s[4:5], 0x0
	s_mov_b32 s4, 10
	s_waitcnt lgkmcnt(0)
	s_ashr_i32 s5, s4, 31
	s_lshl_b64 s[4:5], s[4:5], 3
	s_add_u32 s4, s0, s4
	s_addc_u32 s5, s1, s5
	s_load_dwordx2 s[58:59], s[4:5], 0x0
	s_mov_b32 s4, 11
	s_waitcnt lgkmcnt(0)
	s_ashr_i32 s5, s4, 31
	s_lshl_b64 s[4:5], s[4:5], 3
	s_add_u32 s4, s0, s4
	s_addc_u32 s5, s1, s5
	s_load_dwordx2 s[38:39], s[4:5], 0x0
	s_mov_b32 s4, 12
	s_waitcnt lgkmcnt(0)
	s_ashr_i32 s5, s4, 31
	s_lshl_b64 s[4:5], s[4:5], 3
	s_add_u32 s4, s0, s4
	s_addc_u32 s5, s1, s5
	s_load_dwordx2 s[40:41], s[4:5], 0x0
	s_mov_b32 s4, 13
	s_waitcnt lgkmcnt(0)
	s_ashr_i32 s5, s4, 31
	s_lshl_b64 s[4:5], s[4:5], 3
	s_add_u32 s4, s0, s4
	s_addc_u32 s5, s1, s5
	s_load_dwordx2 s[4:5], s[4:5], 0x0
	s_mov_b32 s42, 14
	s_waitcnt lgkmcnt(0)
	s_ashr_i32 s43, s42, 31
	s_lshl_b64 s[42:43], s[42:43], 3
	s_add_u32 s42, s0, s42
	s_addc_u32 s43, s1, s43
	s_load_dwordx2 s[54:55], s[42:43], 0x0
	s_mov_b32 s42, 15
	s_waitcnt lgkmcnt(0)
	s_ashr_i32 s43, s42, 31
	s_lshl_b64 s[42:43], s[42:43], 3
	s_add_u32 s42, s0, s42
	s_addc_u32 s43, s1, s43
	s_load_dwordx2 s[48:49], s[42:43], 0x0
	s_mov_b32 s42, 16
	s_waitcnt lgkmcnt(0)
	s_ashr_i32 s43, s42, 31
	s_lshl_b64 s[42:43], s[42:43], 3
	s_add_u32 s42, s0, s42
	s_addc_u32 s43, s1, s43
	s_load_dwordx2 s[42:43], s[42:43], 0x0
	s_mov_b32 s46, 17
	s_waitcnt lgkmcnt(0)
	s_ashr_i32 s47, s46, 31
	s_lshl_b64 s[46:47], s[46:47], 3
	s_add_u32 s46, s0, s46
	s_addc_u32 s47, s1, s47
	s_load_dwordx2 s[56:57], s[46:47], 0x0
	s_mov_b32 s46, 18
	s_waitcnt lgkmcnt(0)
	s_ashr_i32 s47, s46, 31
	s_lshl_b64 s[46:47], s[46:47], 3
	s_add_u32 s46, s0, s46
	s_addc_u32 s47, s1, s47
	s_load_dwordx2 s[46:47], s[46:47], 0x0
	s_mov_b32 s50, 19
	s_waitcnt lgkmcnt(0)
	s_ashr_i32 s51, s50, 31
	s_lshl_b64 s[50:51], s[50:51], 3
	s_add_u32 s50, s0, s50
	s_addc_u32 s51, s1, s51
	v_mbcnt_hi_u32_b32 v212, -1, v0
	s_load_dwordx2 s[50:51], s[50:51], 0x0
	v_mov_b32_e32 v32, v212
	s_mov_b32 s45, 0
	s_waitcnt lgkmcnt(0)
	s_cmpk_gt_i32 s26, 0x1f7f
	v_ashrrev_i32_e32 v0, 3, v32
	s_cbranch_scc1 .LBB0_186
; #define LAS __attribute__((address_space(3)))
; __device__ __forceinline__ void tr_item(const float* W, int ldw, int K, int k0, int sc0, bf16* WT, int dr0, const float* gain, float cs, LAS float* scr, int lane) {
; #pragma unroll 16
;     for (int i = 0; i < 32; ++i) { const int kk = 2 * i + (lane >> 5); const float g = gain ? gain[k0 + kk] * cs : cs;
;         scr[kk * 33 + (lane & 31)] = W[(size_t)(k0 + kk) * ldw + sc0 + (lane & 31)] * g; }
; __global__ void __launch_bounds__(NTHR, 2) hybrid_fwd(Args args) {
;     ...
;         const int lane = hw_lane(), tid = wave * 64 + lane;
;         LAS float* scr = (LAS float*)(ldsl + wave * 16384);
;         constexpr int I0 = 16 * 128, I1 = 8 * 32, I2 = 16 * 32, I3 = 16 * 16, I4 = 16 * 32, I5 = 8 * 32, I6 = 16 * 176, I7 = 44 * 32;
;         constexpr int NIT = I0 + I1 + I2 + I3 + I4 + I5 + I6 + I7;
;         for (int rt_ = 0; rt_ < REP_P0T; ++rt_)
;         for (int it = gw; it < NIT; it += NGW) {
;             int r = it;
;             if (r < I0) { const int kb = r / 128, nb = r % 128, n0 = 32 * nb; tr_item(w_in, INC, 1024, 64 * kb, n0 < 2048 ? n0 : n0 + 8, W1t, n0, norm_mix_g, 1.0f, scr, lane); continue; } r -= I0;
;             if (r < I1) { const int kb = r / 32, nb = r % 32; tr_item(w_fox_out, 1024, 1024, 64 * kb, 32 * nb, Wmix + 512, 32 * nb, nullptr, 1.0f, scr, lane); continue; } r -= I1;
;             if (r < I2) { const int kb = r / 32, nb = r % 32; tr_item(w_out, 1024, 1024, 64 * kb, 32 * nb, Wout, 32 * nb, nullptr, 1.0f, scr, lane); continue; } r -= I2;
;             if (r < I3) { const int kb = r / 16, nb = r % 16; tr_item(w_xq, 512, 1024, 64 * kb, 32 * nb, Wxq, 32 * nb, norm_x_g, 0.08838834764831845f * LOG2E, scr, lane); continue; } r -= I3;
;             if (r < I4) { const int kb = r / 32, nb = r % 32; tr_item(w_xkv, 1024, 1024, 64 * kb, 32 * nb, Wxkv, 32 * nb, norm_mem_g, 1.0f, scr, lane); continue; } r -= I4;
;             if (r < I5) { const int kb = r / 32, nb = r % 32; tr_item(w_xo, 1024, 512, 64 * kb, 32 * nb, Wxo, 32 * nb, nullptr, 1.0f, scr, lane); continue; } r -= I5;
;             if (r < I6) { const int kb = r / 176, nb = r % 176, n0 = 32 * nb, j = n0 >> 8, wi = n0 & 255; const int sc = wi < 128 ? 128 * j + wi : DFF + 128 * j + (wi - 128);
;                           tr_item(w_ffn_in, 2 * DFF, 1024, 64 * kb, sc, Wffi, n0, norm_ffn_g, 1.0f, scr, lane); continue; } r -= I6;
	v_lshlrev_b32_e32 v1, 2, v32
	v_and_b32_e32 v44, 0x7c, v1
	v_lshlrev_b32_e32 v1, 3, v32
	s_lshl_b32 s27, s74, 14
	v_mov_b32_e32 v45, 0
	v_and_b32_e32 v1, 56, v1
	s_add_i32 s3, s27, 0
	v_lshlrev_b32_e32 v6, 1, v1
	v_mov_b32_e32 v7, v45
	v_lshl_add_u64 v[4:5], s[46:47], 0, v[44:45]
	v_lshl_add_u64 v[26:27], s[24:25], 0, v[6:7]
	s_mov_b64 s[46:47], 0x1c00000
	s_cmp_lg_u64 s[42:43], 0
	v_lshl_add_u64 v[6:7], v[26:27], 0, s[46:47]
	s_cselect_b64 s[46:47], -1, 0
	s_mov_b64 s[50:51], 0x1100000
	v_lshl_add_u64 v[10:11], s[48:49], 0, v[44:45]
	s_mov_b64 s[48:49], 0x1000000
	s_cmp_lg_u64 s[40:41], 0
	v_lshl_add_u64 v[8:9], v[26:27], 0, s[50:51]
	v_lshl_add_u64 v[12:13], v[26:27], 0, s[48:49]
	s_cselect_b64 s[48:49], -1, 0
	s_mov_b64 s[50:51], 0xe00000
	s_cmp_lg_u64 s[38:39], 0
	v_ashrrev_i32_e32 v2, 5, v32
	v_lshl_add_u64 v[14:15], v[26:27], 0, s[50:51]
	s_cselect_b64 s[50:51], -1, 0
	v_lshl_add_u64 v[22:23], s[52:53], 0, v[44:45]
	s_mov_b64 s[52:53], 0x900400
	s_cmp_lg_u64 s[6:7], 0
	s_movk_i32 s29, 0x84
	v_mul_u32_u24_e32 v3, 0x84, v1
	v_lshlrev_b32_e32 v1, 2, v0
	s_mov_b64 s[62:63], 0xd00000
	v_lshl_add_u64 v[24:25], v[26:27], 0, s[52:53]
	s_cselect_b64 s[52:53], -1, 0
	v_ashrrev_i32_e32 v29, 31, v2
	v_mov_b32_e32 v28, v2
	v_lshl_add_u64 v[40:41], s[4:5], 0, v[44:45]
	s_lshl_b32 s4, s60, 5
	s_lshl_b32 s5, s74, 2
	v_add_u32_e32 v73, s3, v44
	v_add3_u32 v75, s3, v3, v1
	v_lshl_add_u64 v[16:17], v[26:27], 0, s[62:63]
	v_lshl_add_u64 v[18:19], s[58:59], 0, v[44:45]
	s_mov_b64 s[58:59], 0xb00000
	s_lshl_b32 s3, s60, 4
	s_lshl_b32 s21, s74, 1
	v_mul_lo_u32 v118, v2, s29
	v_lshlrev_b64 v[34:35], 2, v[28:29]
	v_lshl_add_u64 v[36:37], s[54:55], 0, v[44:45]
	s_movk_i32 s54, 0xa008
	s_add_i32 s62, s4, s5
	s_mov_b32 s4, 0xffff5008
	v_lshl_add_u64 v[20:21], v[26:27], 0, s[58:59]
	s_mov_b64 s[58:59], 0x100000
	s_add_i32 s3, s3, s21
	v_add_u32_e32 v1, s27, v118
	s_lshl_b32 s27, s60, 8
	s_lshl_b32 s29, s74, 5
	v_lshl_add_u64 v[38:39], s[40:41], 0, v[34:35]
	s_mov_b32 s55, -1
	v_lshl_add_u64 v[42:43], s[38:39], 0, v[34:35]
	s_mov_b32 s5, -1
	v_add_u32_e32 v114, 8, v0
	v_add_u32_e32 v115, 16, v0
	v_add_u32_e32 v116, 24, v0
	v_lshl_add_u64 v[26:27], v[26:27], 0, s[58:59]
	v_add_u32_e32 v117, 0xffffcc00, v2
	s_lshl_b32 s21, s44, 4
	v_add_u32_e32 v119, 0x108, v118
	v_add_u32_e32 v120, 0x210, v118
	v_add_u32_e32 v121, 0x318, v118
	v_add_u32_e32 v122, 0x420, v118
	v_add_u32_e32 v123, 0x528, v118
	v_add_u32_e32 v124, 0x630, v118
	v_add3_u32 v125, v1, v44, 0
	v_lshl_add_u64 v[30:31], s[56:57], 0, v[44:45]
	s_add_i32 s27, s27, s29
	s_lshl_b32 s29, s44, 8
	v_lshl_add_u64 v[38:39], v[38:39], 0, s[54:55]
	s_lshl_b32 s63, s44, 5
	v_lshl_add_u64 v[42:43], v[42:43], 0, s[4:5]
	v_lshl_add_u64 v[44:45], s[10:11], 0, v[44:45]
	s_mov_b32 s64, 0x7fffffc2
	s_movk_i32 s65, 0x1600
	s_movk_i32 s66, 0x5800
	s_mov_b64 s[54:55], 0x80
	s_movk_i32 s67, 0x4020
	s_mov_b32 s68, s3
	s_mov_b32 s69, 0
	s_mov_b32 s70, s26
	v_add_u32_e32 v126, 0x738, v118
	v_add_u32_e32 v127, 0x840, v118
	v_add_u32_e32 v128, 0x948, v118
	v_add_u32_e32 v129, 0xa50, v118
	v_add_u32_e32 v130, 0xb58, v118
	v_add_u32_e32 v131, 0xc60, v118
	v_add_u32_e32 v132, 0xd68, v118
	v_add_u32_e32 v133, 0xe70, v118
	v_add_u32_e32 v134, 0xf78, v118
	v_add_u32_e32 v135, 0x1080, v118
	v_add_u32_e32 v136, 0x1188, v118
	v_add_u32_e32 v137, 0x1290, v118
	v_add_u32_e32 v138, 0x1398, v118
	v_add_u32_e32 v139, 0x14a0, v118
	v_add_u32_e32 v140, 0x15a8, v118
	v_add_u32_e32 v141, 0x16b0, v118
	v_add_u32_e32 v142, 0x17b8, v118
	v_add_u32_e32 v143, 0x18c0, v118
	v_add_u32_e32 v144, 0x19c8, v118
	v_add_u32_e32 v145, 0x1ad0, v118
	v_add_u32_e32 v146, 0x1bd8, v118
	v_add_u32_e32 v147, 0x1ce0, v118
	v_add_u32_e32 v148, 0x1de8, v118
	v_add_u32_e32 v149, 0x1ef0, v118
	v_add_u32_e32 v150, 0x1ff8, v118
	v_add_u32_e32 v151, 0xffffe81e, v2
	v_add_u32_e32 v152, 0xffffe800, v2
	v_add_u32_e32 v153, 0xffffe81c, v2
	v_add_u32_e32 v154, 0xffffe81a, v2
	v_add_u32_e32 v155, 0xffffe818, v2
	v_add_u32_e32 v156, 0xffffe802, v2
	v_add_u32_e32 v157, 0xffffe816, v2
	v_add_u32_e32 v158, 0xffffe804, v2
	v_add_u32_e32 v159, 0xffffe814, v2
	v_add_u32_e32 v160, 0xffffe806, v2
	v_add_u32_e32 v161, 0xffffe812, v2
	v_add_u32_e32 v162, 0xffffe808, v2
	v_add_u32_e32 v163, 0xffffe810, v2
	v_add_u32_e32 v164, 0xffffe80a, v2
	v_add_u32_e32 v165, 0xffffe80e, v2
	v_add_u32_e32 v166, 0xffffe80c, v2
	v_add_u32_e32 v167, 0xffffd41e, v2
	v_add_u32_e32 v168, 0xffffd400, v2
	v_add_u32_e32 v169, 0xffffd41c, v2
	v_add_u32_e32 v170, 0xffffd41a, v2
	v_add_u32_e32 v171, 0xffffd418, v2
	v_add_u32_e32 v172, 0xffffd402, v2
	v_add_u32_e32 v173, 0xffffd416, v2
	v_add_u32_e32 v174, 0xffffd404, v2
	v_add_u32_e32 v175, 0xffffd414, v2
	v_add_u32_e32 v176, 0xffffd406, v2
	v_add_u32_e32 v177, 0xffffd412, v2
	v_add_u32_e32 v178, 0xffffd408, v2
	v_add_u32_e32 v179, 0xffffd410, v2
	v_add_u32_e32 v180, 0xffffd40a, v2
	v_add_u32_e32 v181, 0xffffd40e, v2
	v_add_u32_e32 v182, 0xffffd40c, v2
	v_add_u32_e32 v1, 2, v2
	v_add_u32_e32 v3, 6, v2
	v_add_u32_e32 v46, 4, v2
	v_add_u32_e32 v33, 10, v2
	v_add_u32_e32 v48, 8, v2
	v_add_u32_e32 v47, 14, v2
	v_add_u32_e32 v50, 12, v2
	v_add_u32_e32 v49, 18, v2
	v_add_u32_e32 v52, 16, v2
	v_add_u32_e32 v51, 22, v2
	v_add_u32_e32 v54, 20, v2
	v_add_u32_e32 v53, 26, v2
	v_add_u32_e32 v56, 24, v2
	v_add_u32_e32 v55, 30, v2
	v_add_u32_e32 v58, 28, v2
	v_add_u32_e32 v57, 34, v2
	v_add_u32_e32 v60, 32, v2
	v_add_u32_e32 v59, 38, v2
	v_add_u32_e32 v62, 36, v2
	v_add_u32_e32 v61, 42, v2
	v_add_u32_e32 v64, 40, v2
	v_add_u32_e32 v63, 46, v2
	v_add_u32_e32 v66, 44, v2
	v_add_u32_e32 v65, 50, v2
	v_add_u32_e32 v68, 48, v2
	v_add_u32_e32 v67, 54, v2
	v_add_u32_e32 v70, 52, v2
	v_add_u32_e32 v69, 58, v2
	v_add_u32_e32 v72, 56, v2
	v_add_u32_e32 v71, 62, v2
	v_add_u32_e32 v74, 60, v2
	s_branch .LBB0_18

; __device__ __forceinline__ int hw_lane() { int l = (int)__builtin_amdgcn_mbcnt_hi(~0u, __builtin_amdgcn_mbcnt_lo(~0u, 0u)); asm volatile("" : "+v"(l)); return l; }
; #define LAS __attribute__((address_space(3)))
; __device__ __forceinline__ gptr_t opq_ptr(const void* p) { gptr_t g = (gptr_t)p; asm volatile("" : "+s"(g)); return g; }
; __global__ void __launch_bounds__(NTHR, 2) hybrid_fwd(Args args) {
;     ...
;     if (rep_ == REP_P0 - 1) {
;         volatile LAS int* flagw = (volatile LAS int*)(ldsl + LDS_BYTES - 64);
;         if (wave == 0) { const int l_ = hw_lane(); const unsigned* xt = (const unsigned*)opq_ptr(args.ws) + 2048; const unsigned mine = __hip_atomic_load(xt + blk, __ATOMIC_RELAXED, __HIP_MEMORY_SCOPE_AGENT); int ok = (G % 8 == 0);
;             for (int b2 = l_; b2 < G; b2 += 64) { const unsigned o = __hip_atomic_load(xt + b2, __ATOMIC_RELAXED, __HIP_MEMORY_SCOPE_AGENT); if ((o == mine) != ((b2 & 7) == (blk & 7))) ok = 0; }
;             ok = __all(ok); if (l_ == 0) *flagw = ok; }
;         __syncthreads();
;         use_xcd = __builtin_amdgcn_readfirstlane(*flagw);
;         __syncthreads();
.LBB0_213:
	s_or_b64 exec, exec, s[6:7]
	v_cndmask_b32_e64 v0, 0, 1, s[22:23]
	s_ashr_i32 s3, s2, 31
	v_cmp_ne_u32_e64 s[4:5], 1, v0
	s_andn2_b64 vcc, exec, s[22:23]
	s_barrier
	s_cbranch_vccnz .LBB0_221
	s_and_b32 s6, s20, 7
	s_cmp_eq_u32 s6, 0
	s_cselect_b64 s[10:11], -1, 0
	v_mov_b32_e32 v0, v212
	s_mov_b64 s[6:7], s[18:19]
	s_lshl_b64 s[8:9], s[2:3], 2
	s_add_u32 s8, s6, s8
	s_addc_u32 s9, s7, s9
	v_mov_b32_e32 v1, 0x2000
	global_load_dword v4, v1, s[8:9] sc1
	v_cmp_gt_i32_e32 vcc, s20, v0
	s_and_saveexec_b64 s[14:15], vcc
	s_cbranch_execz .LBB0_218
	v_ashrrev_i32_e32 v1, 31, v0
	v_lshl_add_u64 v[2:3], v[0:1], 2, s[6:7]
	s_mov_b64 s[6:7], 0x2000
	v_cndmask_b32_e64 v5, 0, 1, s[10:11]
	v_lshl_add_u64 v[2:3], v[2:3], 0, s[6:7]
	s_mov_b64 s[22:23], 0
	s_mov_b64 s[24:25], 0x100
	v_mov_b32_e32 v1, v0

; #define PG8_LAS __attribute__((address_space(3)))
; #define PG8_WAIT_V(n) asm volatile("s_waitcnt vmcnt(" #n ")" ::: "memory")
; template <class Epi, class Sched, bool ALIGN_EPI = false, bool SP2 = false>
; __device__ __forceinline__ void gemm_phase(PG8_LAS unsigned char* lds, const Gemm g, const Sched& S, const Epi& E, const int wv) {
;     const int wid = wv, lane = hw_lane(), tid = wid * 64 + lane, wr = wid >> 2, wc = wid & 3, fr = lane & 15, fq = lane >> 4;
;     const int K = g.K, nt = K / BK;
;     unsigned voffA[2], voffB[2];
; #pragma unroll
;     for (int i = 0; i < 2; ++i) { int R, C; stage_rc(tid * 16 + i * 8192, R, C); const int Rb = Epi::PERM ? ((R & ~31) + perm32(R & 31)) : R;
;         voffA[i] = (unsigned)(R * K + C) * 2u; voffB[i] = (unsigned)(Rb * K + C) * 2u; }
;     const size_t kstep = (size_t)(BK * 2);
;     const size_t hstep = (size_t)HALF * K * 2;
;     const size_t tstep = 2 * hstep;
;     const unsigned ldsw = (unsigned)wid * 1024u;
;     const int aoff = lds_byte(wr * 64 + fr, fq * 8), boff = lds_byte(wc * 32 + fr, fq * 8);
;     ...
;     Unit cur, nxt; int ui = 0;
;     if (!S.next(0, cur)) return;
;     f32x4 acc[2][2][4][2];
; #pragma unroll
;     for (int a = 0; a < 2; ++a)
; #pragma unroll
;         for (int b = 0; b < 2; ++b)
; #pragma unroll
;             for (int m = 0; m < 4; ++m)
; #pragma unroll
;                 for (int n = 0; n < 2; ++n) acc[a][b][m][n] = (f32x4){0.f, 0.f, 0.f, 0.f};
;     bf16x8 At[4][2], B0[2][2], B1[2][2];
;     const char* cA = (const char*)g.A + (size_t)cur.pm * tstep; const char* cB = (const char*)g.Bt + (size_t)cur.pn * tstep;
;     S.a_ready(cur);
;     if constexpr (SP2) {
;         PG8_STAGE(PG8_SB(0, 0), cB, voffB); PG8_STAGE(PG8_SB(0, 1), cB + hstep, voffB); PG8_STAGE(PG8_SA(0, 0), cA, voffA); PG8_STAGE(PG8_SA(0, 1), cA + hstep, voffA);
;         if (wr == 1) PG8_BAR;
;         PG8_WAIT_V(2); PG8_BAR;
; __global__ void __launch_bounds__(NTHR, 2) hybrid_fwd(Args args) {
;     ...
;     DECL_PTRS
;     (void)x; (void)mem; (void)out; (void)CC;
;     {
;         const int lane = hw_lane();
;         for (int rb_ = 0; rb_ < REP_P1B; ++rb_)
;         { pg8::Gemm g{XB, W1t, T, 4096, 1024}; pg8::StaticOrder S; S.init(T, 4096, G, blk);
;           epi::InProj E{UB, QF, KF, VF, GT, SSQ0, b_gate};
;           pg8::gemm_phase<epi::InProj, pg8::StaticOrder, PG8_ALIGN, PG8_SP2>(ldsl, g, S, E, wave); }
.LBB0_221:
	s_add_i32 s6, 0, 0x23fc0
	s_lshl_b32 s73, s74, 5
	v_mov_b32_e32 v0, s6
	s_lshr_b32 s6, s72, 8
	s_and_b32 s7, s73, 0x60
	s_lshl_b32 s64, s74, 10
	s_lshl_b32 s66, s6, 6
	s_lshl_b32 s46, s6, 13
	v_writelane_b32 v248, s7, 0
	s_lshr_b32 s7, s7, 3
	s_cmp_eq_u32 s6, 1
	v_writelane_b32 v248, s7, 1
	s_cselect_b64 s[6:7], -1, 0
	s_cmpk_lt_u32 s72, 0x100
	s_cselect_b64 s[22:23], -1, 0
	s_lshr_b32 s9, s3, 29
	s_add_i32 s9, s2, s9
	s_ashr_i32 s67, s9, 3
	s_and_b32 s9, s9, -8
	s_sub_i32 s68, s2, s9
	s_mov_b64 s[10:11], s[18:19]
	s_waitcnt lgkmcnt(0)
	s_barrier
	ds_read_b32 v0, v0
	s_waitcnt lgkmcnt(0)
	s_barrier
	s_ashr_i32 s21, s20, 31
	s_cmp_lt_i32 s68, 0
	s_cselect_b64 s[26:27], -1, 0
	s_waitcnt lgkmcnt(0)
	s_waitcnt lgkmcnt(0)
	s_waitcnt lgkmcnt(0)
	s_waitcnt lgkmcnt(0)
	s_mov_b32 s12, 5
	s_waitcnt lgkmcnt(0)
	s_ashr_i32 s13, s12, 31
	s_lshl_b64 s[8:9], s[12:13], 3
	s_add_u32 s8, s0, s8
	s_addc_u32 s9, s1, s9
	s_load_dwordx2 s[12:13], s[8:9], 0x0
	s_waitcnt lgkmcnt(0)
	s_waitcnt lgkmcnt(0)
	s_waitcnt lgkmcnt(0)
	s_waitcnt lgkmcnt(0)
	s_waitcnt lgkmcnt(0)
	s_waitcnt lgkmcnt(0)
	s_waitcnt lgkmcnt(0)
	s_waitcnt lgkmcnt(0)
	s_waitcnt lgkmcnt(0)
	s_waitcnt lgkmcnt(0)
	s_waitcnt lgkmcnt(0)
	s_waitcnt lgkmcnt(0)
	s_waitcnt lgkmcnt(0)
	s_mov_b32 s14, 19
	s_waitcnt lgkmcnt(0)
	s_ashr_i32 s15, s14, 31
	s_lshl_b64 s[8:9], s[14:15], 3
	s_add_u32 s8, s0, s8
	s_addc_u32 s9, s1, s9
	v_cndmask_b32_e64 v2, 0, 1, s[6:7]
	v_mov_b32_e32 v1, v212
	s_load_dwordx2 s[8:9], s[8:9], 0x0
	v_mov_b32_e32 v8, v212
	v_readfirstlane_b32 s76, v0
	s_cmpk_lt_i32 s2, 0x800
	v_cmp_ne_u32_e64 s[6:7], 1, v2
	s_mov_b32 s69, s46
	v_writelane_b32 v248, s26, 2
	s_waitcnt lgkmcnt(0)
	s_nop 0
	v_writelane_b32 v248, s27, 3
	s_cbranch_scc0 .LBB0_254
	v_lshl_add_u32 v0, v8, 4, s64
	v_add_u32_e32 v1, 0x2000, v0
	v_ashrrev_i32_e32 v2, 31, v1
	v_lshrrev_b32_e32 v2, 22, v2
	v_add_u32_e32 v2, v1, v2
	v_ashrrev_i32_e32 v9, 10, v2
	v_mul_i32_i24_e32 v2, 0x400, v9
	v_sub_u32_e32 v1, v1, v2
	v_lshrrev_b32_e32 v2, 4, v1
	v_bitop3_b32 v1, v2, v1, 32 bitop3:0x6c
	v_ashrrev_i32_e32 v2, 31, v1
	v_lshrrev_b32_e32 v2, 26, v2
	v_add_u32_e32 v2, v1, v2
	v_ashrrev_i32_e32 v10, 6, v2
	v_lshlrev_b32_e32 v3, 3, v9
	v_and_b32_e32 v2, 0xffc0, v2
	v_and_b32_e32 v3, -16, v3
	v_sub_u32_e32 v1, v1, v2
	v_add_u32_e32 v3, v10, v3
	v_lshrrev_b16_e32 v2, 7, v1
	s_waitcnt vmcnt(0)
	v_and_b32_e32 v4, 3, v10
	s_mov_b32 s8, 0x1fffe0
	v_lshrrev_b32_e32 v5, 2, v3
	v_lshlrev_b32_e32 v6, 1, v3
	v_and_b32_e32 v2, 1, v2
	v_and_or_b32 v4, v3, s8, v4
	v_and_b32_e32 v5, 4, v5
	v_and_b32_e32 v6, 24, v6
	v_add_u16_e32 v1, v1, v2
	v_mov_b32_e32 v2, 1
	v_or3_b32 v4, v4, v5, v6
	v_lshlrev_b32_e32 v5, 5, v9
	v_ashrrev_i16_sdwa v1, v2, sext(v1) dst_sel:DWORD dst_unused:UNUSED_PAD src0_sel:DWORD src1_sel:BYTE_0
	v_and_b32_e32 v5, 32, v5
	v_bfe_i32 v11, v1, 0, 16
	v_add_lshl_u32 v1, v5, v11, 1
	v_lshl_add_u32 v144, v4, 11, v1
	v_lshl_add_u32 v146, v3, 11, v1
	v_ashrrev_i32_e32 v1, 31, v0
	v_lshrrev_b32_e32 v1, 22, v1
	v_add_u32_e32 v1, v0, v1
	v_ashrrev_i32_e32 v12, 10, v1
	v_mul_i32_i24_e32 v1, 0x400, v12
	v_sub_u32_e32 v0, v0, v1
	v_lshrrev_b32_e32 v1, 4, v0
	v_bitop3_b32 v0, v1, v0, 32 bitop3:0x6c
	v_ashrrev_i32_e32 v1, 31, v0
	s_add_u32 s77, s10, 0x100000
	v_lshrrev_b32_e32 v1, 26, v1
	s_addc_u32 s78, s11, 0
	v_add_u32_e32 v1, v0, v1
	v_lshlrev_b32_e32 v3, 3, v12
	s_add_u32 s79, s10, 0x3c00000
	v_ashrrev_i32_e32 v13, 6, v1
	v_and_b32_e32 v3, -16, v3
	s_addc_u32 s80, s11, 0
	v_add_u32_e32 v3, v13, v3
	v_and_b32_e32 v4, 3, v13
	s_lshl_b32 s15, s68, 8
	v_and_or_b32 v4, v3, s8, v4
	s_mul_i32 s14, s68, 0x101
	s_and_b64 s[8:9], s[26:27], exec
	s_cselect_b32 s8, s14, s15
	s_add_i32 s8, s8, s67
	s_ashr_i32 s9, s8, 31
	s_lshr_b32 s9, s9, 25
	s_add_i32 s9, s8, s9
	s_ashr_i32 s14, s9, 7
	s_and_b32 s9, s9, 0xff80
	s_sub_i32 s9, s8, s9
	s_bfe_i32 s8, s9, 0x80000
	s_bfe_u32 s8, s8, 0x3000c
	s_add_i32 s15, s9, s8
	s_bfe_i32 s8, s15, 0x80000
	s_and_b32 s15, s15, 0xf8
	s_sub_i32 s9, s9, s15
	s_lshl_b32 s14, s14, 3
	s_sext_i32_i16 s8, s8
	s_sext_i32_i8 s9, s9
	v_lshrrev_b32_e32 v5, 2, v3
	v_lshlrev_b32_e32 v6, 1, v3
	v_and_b32_e32 v1, 0xc0, v1
	s_lshr_b32 s8, s8, 3
	s_add_i32 s56, s14, s9
	v_and_b32_e32 v5, 4, v5
	v_and_b32_e32 v6, 24, v6
	v_sub_u32_e32 v0, v0, v1
	s_ashr_i32 s57, s56, 31
	s_bfe_i64 s[24:25], s[8:9], 0x100000
	v_or3_b32 v4, v4, v5, v6
	v_lshlrev_b32_e32 v5, 5, v12
	v_ashrrev_i16_sdwa v0, v2, sext(v0) dst_sel:DWORD dst_unused:UNUSED_PAD src0_sel:DWORD src1_sel:BYTE_0
	s_lshl_b64 s[14:15], s[56:57], 19
	s_lshl_b64 s[24:25], s[24:25], 19
	v_and_b32_e32 v5, 32, v5
	v_bfe_i32 v14, v0, 0, 16
	s_add_u32 s60, s77, s24
	v_add_lshl_u32 v0, v5, v14, 1
	s_addc_u32 s61, s78, s25
	s_add_i32 s81, s64, 0
	v_lshl_add_u32 v148, v4, 11, v0
	s_add_i32 m0, s81, 0x10000
	v_lshl_add_u32 v150, v3, 11, v0
	global_load_lds_dwordx4 v148, s[60:61]
	s_add_i32 m0, s81, 0x12000
	s_add_u32 s24, s60, 0x40000
	global_load_lds_dwordx4 v144, s[60:61]
	s_addc_u32 s25, s61, 0
	s_add_i32 m0, s81, 0x14000
	v_mov_b32_e32 v149, 0
	global_load_lds_dwordx4 v148, s[24:25]
	s_add_i32 m0, s81, 0x16000
	s_add_u32 s58, s79, s14
	s_addc_u32 s59, s80, s15
	s_add_i32 s82, s81, 0x2000
	global_load_lds_dwordx4 v144, s[24:25]
	s_mov_b32 m0, s81
	s_add_u32 s14, s58, 0x40000
	global_load_lds_dwordx4 v150, s[58:59]
	s_mov_b32 m0, s82
	s_addc_u32 s15, s59, 0
	s_add_i32 s83, s81, 0x4000
	global_load_lds_dwordx4 v146, s[58:59]
	s_mov_b32 m0, s83
	s_add_i32 s84, s81, 0x6000
	global_load_lds_dwordx4 v150, s[14:15]
	s_mov_b32 m0, s84
	v_mov_b32_e32 v145, v149
	global_load_lds_dwordx4 v146, s[14:15]
	v_mov_b32_e32 v151, v149
	v_mov_b32_e32 v147, v149
	v_lshl_add_u64 v[6:7], s[60:61], 0, v[148:149]
	v_lshl_add_u64 v[4:5], s[60:61], 0, v[144:145]
	v_lshl_add_u64 v[2:3], s[58:59], 0, v[150:151]
	s_and_b64 vcc, exec, s[6:7]
	v_lshl_add_u64 v[0:1], s[58:59], 0, v[146:147]
	s_cbranch_vccnz .LBB0_224
	s_barrier

; __device__ __forceinline__ int hw_lane() { int l = (int)__builtin_amdgcn_mbcnt_hi(~0u, __builtin_amdgcn_mbcnt_lo(~0u, 0u)); asm volatile("" : "+v"(l)); return l; }
; __global__ void __launch_bounds__(NTHR, 2) hybrid_fwd(Args args) {
;     ...
;     for (int rep_ = 0; rep_ < REP_P2; ++rep_) {
;     DECL_PTRS
;     (void)x; (void)mem; (void)out; (void)CC;
;     {
;         const int lane = hw_lane();
;         const int rpb = (T + G - 1) / G, rows_per = (rpb + NWAVES - 1) / NWAVES;
;         const int gI = lane >> 4, w = 2 << gI;
;         const int t_b = hb * rpb + wave * rows_per; int nr = rpb - wave * rows_per; if (nr > rows_per) nr = rows_per; if (t_b + nr > T) nr = T - t_b;
.LBB0_370:
	s_mov_b64 s[8:9], s[18:19]
	s_mov_b32 s11, s20
	s_and_b32 s14, s11, 7
	s_mov_b32 s24, s2
	s_cmp_lg_u32 s14, 0
	s_cbranch_scc1 .LBB0_372
	s_ashr_i32 s15, s24, 31
	s_lshr_b32 s15, s15, 29
	s_add_i32 s15, s24, s15
	s_ashr_i32 s25, s15, 3
	s_and_b32 s15, s15, -8
	s_ashr_i32 s11, s11, 3
	s_sub_i32 s15, s24, s15
	s_mul_i32 s11, s15, s11
	s_add_i32 s24, s11, s25
.LBB0_372:
	s_add_i32 s25, s20, 0x7fff
	s_waitcnt lgkmcnt(0)
	s_waitcnt lgkmcnt(0)
	s_waitcnt lgkmcnt(0)
	s_waitcnt lgkmcnt(0)
	s_waitcnt lgkmcnt(0)
	s_waitcnt lgkmcnt(0)
	s_waitcnt lgkmcnt(0)
	s_waitcnt lgkmcnt(0)
	s_waitcnt lgkmcnt(0)
	s_waitcnt lgkmcnt(0)
	s_waitcnt lgkmcnt(0)
	s_waitcnt lgkmcnt(0)
	s_waitcnt lgkmcnt(0)
	s_waitcnt lgkmcnt(0)
	s_waitcnt lgkmcnt(0)
	s_waitcnt lgkmcnt(0)
	s_waitcnt lgkmcnt(0)
	s_waitcnt lgkmcnt(0)
	s_waitcnt lgkmcnt(0)
	s_abs_i32 s61, s20
	v_cvt_f32_u32_e32 v1, s61
	s_sub_i32 s27, 0, s61
	s_waitcnt lgkmcnt(0)
	v_rcp_iflag_f32_e32 v1, v1
	s_ashr_i32 s26, s25, 31
	s_abs_i32 s25, s25
	v_mul_f32_e32 v1, 0x4f7ffffe, v1
	v_cvt_u32_f32_e32 v1, v1
	s_xor_b32 s26, s26, s21
	s_mov_b32 s28, 1
	v_readfirstlane_b32 s62, v1
	s_mul_i32 s27, s27, s62
	s_mul_hi_u32 s10, s62, s27
	s_add_i32 s62, s62, s10
	s_mul_hi_u32 s10, s25, s62
	s_mul_i32 s11, s10, s61
	s_sub_i32 s11, s25, s11
	s_add_i32 s14, s10, 1
	s_sub_i32 s15, s11, s61
	s_cmp_ge_u32 s11, s61
	s_cselect_b32 s10, s14, s10
	s_cselect_b32 s11, s15, s11
	s_add_i32 s14, s10, 1
	s_cmp_ge_u32 s11, s61
	s_cselect_b32 s10, s14, s10
	s_xor_b32 s10, s10, s26
	s_sub_i32 s56, s10, s26
	s_add_i32 s10, s56, 7
	s_ashr_i32 s14, s10, 31
	s_lshr_b32 s14, s14, 29
	s_add_i32 s10, s10, s14
	s_ashr_i32 s14, s10, 3
	s_mul_i32 s11, s56, s24
	s_mul_i32 s15, s14, s74
	s_add_i32 s10, s15, s11
	s_sub_i32 s11, s56, s15
	s_min_i32 s57, s11, s14
	s_add_i32 s11, s57, s10
	s_sub_i32 s14, 0x8000, s10
	s_cmp_gt_i32 s11, 0x8000
	s_cselect_b32 s29, s14, s57
	v_mov_b32_e32 v0, v212
	s_cmp_lt_i32 s29, 1
	v_writelane_b32 v248, s15, 5
	s_cbranch_scc1 .LBB0_377
; __global__ void __launch_bounds__(NTHR, 2) hybrid_fwd(Args args) {
;     ...
;         if (nr > 0) { const int sp0 = t_b & 2047, c0_ = (sp0 + 1) < w ? (sp0 + 1) : w;
; #pragma unroll
;             for (int j = 0; j < 16; ++j) qn[j] = *(const u32x4*)(UB + (size_t)(j < c0_ ? t_b - j : t_b) * 512 + lane * 8); }
;     ...
;             for (int j = 0; j < 16; ++j) qv[j] = qn[j];
	v_ashrrev_i32_e32 v1, 4, v0
	s_and_b32 s11, s10, 0x7ff
	v_lshlrev_b32_e64 v132, v1, 2
	s_add_i32 s11, s11, 1
	v_min_i32_e32 v6, s11, v132
	v_lshlrev_b32_e32 v0, 3, v0
	v_ashrrev_i32_e32 v1, 31, v0
	s_waitcnt vmcnt(0)
	v_mov_b32_e32 v4, s10
	v_cmp_lt_i32_e32 vcc, 1, v6
	v_lshl_add_u64 v[0:1], v[0:1], 1, s[8:9]
	s_mov_b64 s[14:15], 0x15c00000
	s_ashr_i32 s11, s10, 31
	v_subbrev_co_u32_e32 v4, vcc, 0, v4, vcc
	v_lshl_add_u64 v[128:129], v[0:1], 0, s[14:15]
	s_lshl_b64 s[14:15], s[10:11], 10
	v_ashrrev_i32_e32 v5, 31, v4
	v_lshl_add_u64 v[2:3], v[128:129], 0, s[14:15]
	v_lshlrev_b64 v[4:5], 10, v[4:5]
	v_cmp_lt_i32_e32 vcc, 2, v6
	v_lshl_add_u64 v[4:5], v[128:129], 0, v[4:5]
	global_load_dwordx4 v[124:127], v[2:3], off
	global_load_dwordx4 v[120:123], v[4:5], off
	v_cndmask_b32_e64 v2, 0, -2, vcc
	v_cmp_lt_i32_e32 vcc, 3, v6
	v_add_u32_e32 v2, s10, v2
	v_ashrrev_i32_e32 v3, 31, v2
	v_cndmask_b32_e64 v4, 0, -3, vcc
	v_add_u32_e32 v4, s10, v4
	v_lshlrev_b64 v[2:3], 10, v[2:3]
	v_ashrrev_i32_e32 v5, 31, v4
	v_lshl_add_u64 v[2:3], v[128:129], 0, v[2:3]
	v_lshlrev_b64 v[4:5], 10, v[4:5]
	v_cmp_lt_i32_e32 vcc, 4, v6
	v_lshl_add_u64 v[4:5], v[128:129], 0, v[4:5]
	global_load_dwordx4 v[116:119], v[2:3], off
	global_load_dwordx4 v[112:115], v[4:5], off
	v_cndmask_b32_e64 v2, 0, -4, vcc
	v_cmp_lt_i32_e32 vcc, 5, v6
	v_add_u32_e32 v2, s10, v2
	v_ashrrev_i32_e32 v3, 31, v2
	v_cndmask_b32_e64 v4, 0, -5, vcc
	v_add_u32_e32 v4, s10, v4
	v_lshlrev_b64 v[2:3], 10, v[2:3]
	v_ashrrev_i32_e32 v5, 31, v4
	v_lshl_add_u64 v[2:3], v[128:129], 0, v[2:3]
	v_lshlrev_b64 v[4:5], 10, v[4:5]
	v_cmp_lt_i32_e32 vcc, 6, v6
	v_lshl_add_u64 v[4:5], v[128:129], 0, v[4:5]
	global_load_dwordx4 v[108:111], v[2:3], off
	global_load_dwordx4 v[104:107], v[4:5], off
	v_cndmask_b32_e64 v2, 0, -6, vcc
	v_cmp_lt_i32_e32 vcc, 7, v6
	v_add_u32_e32 v2, s10, v2
	v_ashrrev_i32_e32 v3, 31, v2
	v_cndmask_b32_e64 v4, 0, -7, vcc
	v_add_u32_e32 v4, s10, v4
	v_lshlrev_b64 v[2:3], 10, v[2:3]
	v_ashrrev_i32_e32 v5, 31, v4
	v_lshl_add_u64 v[2:3], v[128:129], 0, v[2:3]
	v_lshlrev_b64 v[4:5], 10, v[4:5]
	v_cmp_lt_i32_e32 vcc, 8, v6
	v_lshl_add_u64 v[4:5], v[128:129], 0, v[4:5]
	global_load_dwordx4 v[100:103], v[2:3], off
	global_load_dwordx4 v[96:99], v[4:5], off
	v_cndmask_b32_e64 v2, 0, -8, vcc
	v_cmp_lt_i32_e32 vcc, 9, v6
	v_add_u32_e32 v2, s10, v2
	v_ashrrev_i32_e32 v3, 31, v2
	v_cndmask_b32_e64 v4, 0, -9, vcc
	v_add_u32_e32 v4, s10, v4
	v_lshlrev_b64 v[2:3], 10, v[2:3]
	v_ashrrev_i32_e32 v5, 31, v4
	v_lshl_add_u64 v[2:3], v[128:129], 0, v[2:3]
	v_lshlrev_b64 v[4:5], 10, v[4:5]
	v_cmp_lt_i32_e32 vcc, 10, v6
	v_lshl_add_u64 v[4:5], v[128:129], 0, v[4:5]
	global_load_dwordx4 v[88:91], v[2:3], off
	global_load_dwordx4 v[92:95], v[4:5], off
	v_cndmask_b32_e64 v2, 0, -10, vcc
	v_cmp_lt_i32_e32 vcc, 11, v6
	v_add_u32_e32 v2, s10, v2
	v_ashrrev_i32_e32 v3, 31, v2
	v_cndmask_b32_e64 v4, 0, -11, vcc
	v_add_u32_e32 v4, s10, v4
	v_lshlrev_b64 v[2:3], 10, v[2:3]
	v_ashrrev_i32_e32 v5, 31, v4
	v_lshl_add_u64 v[2:3], v[128:129], 0, v[2:3]
	v_lshlrev_b64 v[4:5], 10, v[4:5]
	v_cmp_lt_i32_e32 vcc, 12, v6
	v_lshl_add_u64 v[4:5], v[128:129], 0, v[4:5]
	global_load_dwordx4 v[64:67], v[2:3], off
	global_load_dwordx4 v[68:71], v[4:5], off
	v_cndmask_b32_e64 v2, 0, -12, vcc
	v_cmp_lt_i32_e32 vcc, 13, v6
	v_add_u32_e32 v2, s10, v2
	v_ashrrev_i32_e32 v3, 31, v2
	v_cndmask_b32_e64 v4, 0, -13, vcc
	v_add_u32_e32 v4, s10, v4
	v_lshlrev_b64 v[2:3], 10, v[2:3]
	v_ashrrev_i32_e32 v5, 31, v4
	v_lshl_add_u64 v[2:3], v[128:129], 0, v[2:3]
	v_lshlrev_b64 v[4:5], 10, v[4:5]
	v_cmp_lt_i32_e32 vcc, 14, v6
	v_lshl_add_u64 v[4:5], v[128:129], 0, v[4:5]
	global_load_dwordx4 v[40:43], v[2:3], off
	global_load_dwordx4 v[44:47], v[4:5], off
	v_cndmask_b32_e64 v2, 0, -14, vcc
	v_cmp_lt_i32_e32 vcc, 15, v6
	v_add_u32_e32 v2, s10, v2
	v_ashrrev_i32_e32 v3, 31, v2
	v_cndmask_b32_e64 v4, 0, -15, vcc
	v_add_u32_e32 v4, s10, v4
	v_lshlrev_b64 v[2:3], 10, v[2:3]
	v_ashrrev_i32_e32 v5, 31, v4
	v_lshl_add_u64 v[2:3], v[128:129], 0, v[2:3]
	v_lshlrev_b64 v[4:5], 10, v[4:5]
	v_lshl_add_u64 v[4:5], v[128:129], 0, v[4:5]
	global_load_dwordx4 v[16:19], v[2:3], off
	global_load_dwordx4 v[20:23], v[4:5], off
	s_mov_b64 s[14:15], 0x3c00000
	v_lshl_add_u64 v[130:131], v[0:1], 0, s[14:15]
	v_cmp_lt_i32_e32 vcc, 0, v132
	s_waitcnt vmcnt(15)
	v_mov_b64_e32 v[0:1], v[124:125]
	s_waitcnt vmcnt(14)
	v_mov_b64_e32 v[4:5], v[120:121]
	s_waitcnt vmcnt(13)
	v_mov_b64_e32 v[8:9], v[116:117]
	s_waitcnt vmcnt(12)
	v_mov_b64_e32 v[12:13], v[112:113]
	v_cndmask_b32_e64 v133, 0, 1.0, vcc
	v_mov_b64_e32 v[2:3], v[126:127]
	v_mov_b64_e32 v[6:7], v[122:123]
	v_mov_b64_e32 v[10:11], v[118:119]
	v_mov_b64_e32 v[14:15], v[114:115]
	s_waitcnt vmcnt(11)
	v_mov_b64_e32 v[24:25], v[108:109]
	s_waitcnt vmcnt(10)
	v_mov_b64_e32 v[28:29], v[104:105]
	v_mov_b64_e32 v[26:27], v[110:111]
	v_mov_b64_e32 v[30:31], v[106:107]
	s_waitcnt vmcnt(9)
	v_mov_b64_e32 v[32:33], v[100:101]
	s_waitcnt vmcnt(8)
	v_mov_b64_e32 v[36:37], v[96:97]
	v_mov_b64_e32 v[34:35], v[102:103]
	v_mov_b64_e32 v[38:39], v[98:99]
	s_waitcnt vmcnt(7)
	v_mov_b64_e32 v[48:49], v[88:89]
	s_waitcnt vmcnt(6)
	v_mov_b64_e32 v[52:53], v[92:93]
	v_mov_b64_e32 v[50:51], v[90:91]
	v_mov_b64_e32 v[54:55], v[94:95]
	s_waitcnt vmcnt(5)
	v_mov_b64_e32 v[56:57], v[64:65]
	s_waitcnt vmcnt(4)
	v_mov_b64_e32 v[60:61], v[68:69]
	v_mov_b64_e32 v[58:59], v[66:67]
	v_mov_b64_e32 v[62:63], v[70:71]
	s_waitcnt vmcnt(3)
	v_mov_b64_e32 v[74:75], v[42:43]
	s_waitcnt vmcnt(2)
	v_mov_b64_e32 v[78:79], v[46:47]
	v_mov_b64_e32 v[72:73], v[40:41]
	v_mov_b64_e32 v[76:77], v[44:45]
	s_waitcnt vmcnt(1)
	v_mov_b64_e32 v[82:83], v[18:19]
	s_waitcnt vmcnt(0)
	v_mov_b64_e32 v[86:87], v[22:23]
	v_mov_b64_e32 v[80:81], v[16:17]
	v_mov_b64_e32 v[84:85], v[20:21]
	s_branch .LBB0_375

; #define PG8_LAS __attribute__((address_space(3)))
; #define PG8_WAIT_V(n) asm volatile("s_waitcnt vmcnt(" #n ")" ::: "memory")
; template <class Epi, class Sched, bool ALIGN_EPI = false, bool SP2 = false>
; __device__ __forceinline__ void gemm_phase(PG8_LAS unsigned char* lds, const Gemm g, const Sched& S, const Epi& E, const int wv) {
;     const int wid = wv, lane = hw_lane(), tid = wid * 64 + lane, wr = wid >> 2, wc = wid & 3, fr = lane & 15, fq = lane >> 4;
;     const int K = g.K, nt = K / BK;
;     unsigned voffA[2], voffB[2];
; #pragma unroll
;     for (int i = 0; i < 2; ++i) { int R, C; stage_rc(tid * 16 + i * 8192, R, C); const int Rb = Epi::PERM ? ((R & ~31) + perm32(R & 31)) : R;
;         voffA[i] = (unsigned)(R * K + C) * 2u; voffB[i] = (unsigned)(Rb * K + C) * 2u; }
;     const size_t kstep = (size_t)(BK * 2);
;     const size_t hstep = (size_t)HALF * K * 2;
;     const size_t tstep = 2 * hstep;
;     const unsigned ldsw = (unsigned)wid * 1024u;
;     const int aoff = lds_byte(wr * 64 + fr, fq * 8), boff = lds_byte(wc * 32 + fr, fq * 8);
;     ...
;     Unit cur, nxt; int ui = 0;
;     if (!S.next(0, cur)) return;
;     f32x4 acc[2][2][4][2];
; #pragma unroll
;     for (int a = 0; a < 2; ++a)
; #pragma unroll
;         for (int b = 0; b < 2; ++b)
; #pragma unroll
;             for (int m = 0; m < 4; ++m)
; #pragma unroll
;                 for (int n = 0; n < 2; ++n) acc[a][b][m][n] = (f32x4){0.f, 0.f, 0.f, 0.f};
;     bf16x8 At[4][2], B0[2][2], B1[2][2];
;     const char* cA = (const char*)g.A + (size_t)cur.pm * tstep; const char* cB = (const char*)g.Bt + (size_t)cur.pn * tstep;
;     S.a_ready(cur);
;     if constexpr (SP2) {
;         PG8_STAGE(PG8_SB(0, 0), cB, voffB); PG8_STAGE(PG8_SB(0, 1), cB + hstep, voffB); PG8_STAGE(PG8_SA(0, 0), cA, voffA); PG8_STAGE(PG8_SA(0, 1), cA + hstep, voffA);
;         if (wr == 1) PG8_BAR;
;         PG8_WAIT_V(2); PG8_BAR;
;         PG8_STAGE(PG8_SB(1, 0), cB + kstep, voffB); PG8_STAGE(PG8_SA(1, 0), cA + kstep, voffA); PG8_STAGE(PG8_SB(1, 1), cB + hstep + kstep, voffB);
;         PG8_WAIT_V(6); PG8_BAR;
;     } else {
; __global__ void __launch_bounds__(NTHR, 2) hybrid_fwd(Args args) {
;     ...
;     { pg8::Gemm g{AD, Wmix, T, 1024, 1024}; pg8::StaticOrder S; S.init(T, 1024, G, blk);
;       epi::Mix E{GT, ZB};
;       pg8::gemm_phase<epi::Mix, pg8::StaticOrder, PG8_ALIGN, PG8_SP2>(ldsl, g, S, E, wave); }
.LBB0_499:
	s_mov_b64 s[8:9], s[18:19]
	s_cmpk_lt_i32 s2, 0x200
	s_cselect_b64 s[14:15], -1, 0
	s_waitcnt lgkmcnt(0)
	s_waitcnt lgkmcnt(0)
	s_waitcnt lgkmcnt(0)
	s_waitcnt lgkmcnt(0)
	s_waitcnt lgkmcnt(0)
	s_waitcnt lgkmcnt(0)
	s_waitcnt lgkmcnt(0)
	s_waitcnt lgkmcnt(0)
	s_waitcnt lgkmcnt(0)
	s_waitcnt lgkmcnt(0)
	s_waitcnt lgkmcnt(0)
	s_waitcnt lgkmcnt(0)
	s_waitcnt lgkmcnt(0)
	s_waitcnt lgkmcnt(0)
	s_waitcnt lgkmcnt(0)
	s_waitcnt lgkmcnt(0)
	s_waitcnt lgkmcnt(0)
	s_waitcnt lgkmcnt(0)
	s_waitcnt lgkmcnt(0)
	s_mov_b64 s[24:25], s[16:17]
	v_mov_b32_e32 v9, v212
	s_cmpk_gt_i32 s2, 0x1ff
	s_mul_i32 s60, s68, 0x41
	s_waitcnt lgkmcnt(0)
	s_cbranch_scc1 .LBB0_521
	v_lshl_add_u32 v0, v9, 4, s64
	v_add_u32_e32 v1, 0x2000, v0
	v_ashrrev_i32_e32 v2, 31, v1
	v_lshrrev_b32_e32 v2, 22, v2
	v_add_u32_e32 v2, v1, v2
	v_ashrrev_i32_e32 v8, 10, v2
	v_mul_i32_i24_e32 v2, 0x400, v8
	v_sub_u32_e32 v1, v1, v2
	v_lshrrev_b32_e32 v2, 4, v1
	v_bitop3_b32 v1, v2, v1, 32 bitop3:0x6c
	v_ashrrev_i32_e32 v2, 31, v1
	v_lshrrev_b32_e32 v2, 26, v2
	v_add_u32_e32 v2, v1, v2
	v_ashrrev_i32_e32 v10, 6, v2
	v_lshlrev_b32_e32 v3, 3, v8
	v_and_b32_e32 v2, 0xffc0, v2
	v_and_b32_e32 v3, -16, v3
	v_sub_u32_e32 v1, v1, v2
	v_add_u32_e32 v3, v10, v3
	v_lshrrev_b16_e32 v2, 7, v1
	v_and_b32_e32 v4, 3, v10
	s_mov_b32 s10, 0x1fffe0
	v_lshrrev_b32_e32 v5, 2, v3
	v_lshlrev_b32_e32 v6, 1, v3
	v_and_b32_e32 v2, 1, v2
	v_and_or_b32 v4, v3, s10, v4
	v_and_b32_e32 v5, 4, v5
	v_and_b32_e32 v6, 24, v6
	v_add_u16_e32 v1, v1, v2
	v_mov_b32_e32 v2, 1
	v_or3_b32 v4, v4, v5, v6
	v_lshlrev_b32_e32 v5, 5, v8
	v_ashrrev_i16_sdwa v1, v2, sext(v1) dst_sel:DWORD dst_unused:UNUSED_PAD src0_sel:DWORD src1_sel:BYTE_0
	v_and_b32_e32 v5, 32, v5
	v_bfe_i32 v11, v1, 0, 16
	v_add_lshl_u32 v1, v5, v11, 1
	v_lshl_add_u32 v168, v4, 11, v1
	v_lshl_add_u32 v170, v3, 11, v1
	v_ashrrev_i32_e32 v1, 31, v0
	v_lshrrev_b32_e32 v1, 22, v1
	v_add_u32_e32 v1, v0, v1
	v_ashrrev_i32_e32 v12, 10, v1
	v_mul_i32_i24_e32 v1, 0x400, v12
	v_sub_u32_e32 v0, v0, v1
	v_lshrrev_b32_e32 v1, 4, v0
	v_bitop3_b32 v0, v1, v0, 32 bitop3:0x6c
	v_ashrrev_i32_e32 v1, 31, v0
	s_add_u32 s52, s8, 0x900000
	v_lshrrev_b32_e32 v1, 26, v1
	s_addc_u32 s53, s9, 0
	v_add_u32_e32 v1, v0, v1
	v_lshlrev_b32_e32 v3, 3, v12
	s_add_u32 s63, s8, 0x3c00000
	v_ashrrev_i32_e32 v13, 6, v1
	v_and_b32_e32 v3, -16, v3
	s_addc_u32 s74, s9, 0
	v_add_u32_e32 v3, v13, v3
	v_and_b32_e32 v4, 3, v13
	s_lshl_b32 s24, s68, 6
	v_and_or_b32 v4, v3, s10, v4
	s_and_b64 s[10:11], s[94:95], exec
	s_cselect_b32 s10, s60, s24
	s_add_i32 s10, s10, s67
	s_ashr_i32 s11, s10, 31
	s_lshr_b32 s11, s11, 27
	s_add_i32 s11, s10, s11
	s_ashr_i32 s24, s11, 5
	s_and_b32 s11, s11, 0xffe0
	s_sub_i32 s10, s10, s11
	s_bfe_i32 s11, s10, 0x80000
	s_bfe_u32 s11, s11, 0x3000c
	s_add_i32 s11, s10, s11
	s_bfe_i32 s25, s11, 0x80000
	s_and_b32 s11, s11, 0xf8
	s_sub_i32 s10, s10, s11
	s_lshl_b32 s24, s24, 3
	s_sext_i32_i16 s25, s25
	s_sext_i32_i8 s10, s10
	v_lshrrev_b32_e32 v5, 2, v3
	v_lshlrev_b32_e32 v6, 1, v3
	v_and_b32_e32 v1, 0xc0, v1
	s_lshr_b32 s30, s25, 3
	s_add_i32 s44, s24, s10
	v_and_b32_e32 v5, 4, v5
	v_and_b32_e32 v6, 24, v6
	v_sub_u32_e32 v0, v0, v1
	s_ashr_i32 s45, s44, 31
	s_bfe_i64 s[24:25], s[30:31], 0x100000
	v_or3_b32 v4, v4, v5, v6
	v_lshlrev_b32_e32 v5, 5, v12
	v_ashrrev_i16_sdwa v0, v2, sext(v0) dst_sel:DWORD dst_unused:UNUSED_PAD src0_sel:DWORD src1_sel:BYTE_0
	s_lshl_b64 s[10:11], s[44:45], 19
	s_lshl_b64 s[24:25], s[24:25], 19
	v_and_b32_e32 v5, 32, v5
	v_bfe_i32 v14, v0, 0, 16
	s_add_u32 s46, s52, s24
	v_add_lshl_u32 v0, v5, v14, 1
	s_addc_u32 s47, s53, s25
	s_add_i32 s75, s64, 0
	v_lshl_add_u32 v172, v4, 11, v0
	s_add_i32 m0, s75, 0x10000
	v_lshl_add_u32 v174, v3, 11, v0
	global_load_lds_dwordx4 v172, s[46:47]
	s_add_i32 m0, s75, 0x12000
	s_add_u32 s24, s46, 0x40000
	global_load_lds_dwordx4 v168, s[46:47]
	s_addc_u32 s25, s47, 0
	s_add_i32 m0, s75, 0x14000
	v_mov_b32_e32 v173, 0
	global_load_lds_dwordx4 v172, s[24:25]
	s_add_i32 m0, s75, 0x16000
	s_add_u32 s42, s63, s10
	s_addc_u32 s43, s74, s11
	s_add_i32 s76, s75, 0x2000
	global_load_lds_dwordx4 v168, s[24:25]
	s_mov_b32 m0, s75
	s_add_u32 s10, s42, 0x40000
	global_load_lds_dwordx4 v174, s[42:43]
	s_mov_b32 m0, s76
	s_addc_u32 s11, s43, 0
	s_add_i32 s77, s75, 0x4000
	global_load_lds_dwordx4 v170, s[42:43]
	s_mov_b32 m0, s77
	s_add_i32 s78, s75, 0x6000
	global_load_lds_dwordx4 v174, s[10:11]
	s_mov_b32 m0, s78
	v_mov_b32_e32 v169, v173
	global_load_lds_dwordx4 v170, s[10:11]
	v_mov_b32_e32 v175, v173
	v_mov_b32_e32 v171, v173
	v_lshl_add_u64 v[6:7], s[46:47], 0, v[172:173]
	v_lshl_add_u64 v[4:5], s[46:47], 0, v[168:169]
	v_lshl_add_u64 v[2:3], s[42:43], 0, v[174:175]
	s_and_b64 vcc, exec, s[6:7]
	v_lshl_add_u64 v[0:1], s[42:43], 0, v[170:171]
	s_cbranch_vccnz .LBB0_502
	s_barrier

; __global__ void __launch_bounds__(NTHR, 2) hybrid_fwd(Args args) {
;     ...
;     { pg8::Gemm g{ZB, Wout, T, 1024, 1024}; pg8::StaticOrder S; S.init(T, 1024, G, blk);
;       epi::Resid<false> E{x, X1B, SSQ1};
;       pg8::gemm_phase<epi::Resid<false>, pg8::StaticOrder, PG8_ALIGN, PG8_SP2>(ldsl, g, S, E, wave); }
.LBB0_542:
	s_mov_b64 s[12:13], s[18:19]
	s_mov_b32 s10, 0
	s_ashr_i32 s11, s10, 31
	s_lshl_b64 s[10:11], s[10:11], 3
	s_add_u32 s10, s0, s10
	s_addc_u32 s11, s1, s11
	s_load_dwordx2 s[26:27], s[10:11], 0x0
	s_waitcnt lgkmcnt(0)
	s_waitcnt lgkmcnt(0)
	s_waitcnt lgkmcnt(0)
	s_waitcnt lgkmcnt(0)
	s_waitcnt lgkmcnt(0)
	s_waitcnt lgkmcnt(0)
	s_waitcnt lgkmcnt(0)
	s_waitcnt lgkmcnt(0)
	s_waitcnt lgkmcnt(0)
	s_waitcnt lgkmcnt(0)
	s_waitcnt lgkmcnt(0)
	s_waitcnt lgkmcnt(0)
	s_waitcnt lgkmcnt(0)
	s_waitcnt lgkmcnt(0)
	s_waitcnt lgkmcnt(0)
	s_waitcnt lgkmcnt(0)
	s_waitcnt lgkmcnt(0)
	s_waitcnt lgkmcnt(0)
	s_mov_b32 s24, 19
	s_waitcnt lgkmcnt(0)
	s_ashr_i32 s25, s24, 31
	s_lshl_b64 s[10:11], s[24:25], 3
	s_add_u32 s10, s0, s10
	s_addc_u32 s11, s1, s11
	s_mov_b64 s[28:29], s[16:17]
	s_load_dwordx2 s[24:25], s[10:11], 0x0
	v_cndmask_b32_e64 v0, 0, 1, s[14:15]
	v_mov_b32_e32 v8, v212
	v_cmp_ne_u32_e64 s[10:11], 1, v0
	s_andn2_b64 vcc, exec, s[14:15]
	s_waitcnt lgkmcnt(0)
	s_cbranch_vccnz .LBB0_544
	s_lshl_b32 s24, s68, 6
	s_and_b64 s[14:15], s[94:95], exec
	s_cselect_b32 s14, s60, s24
	s_add_i32 s14, s14, s67
	s_ashr_i32 s15, s14, 31
	s_lshr_b32 s15, s15, 27
	s_add_i32 s15, s14, s15
	s_ashr_i32 s24, s15, 5
	s_and_b32 s15, s15, 0xffe0
	s_sub_i32 s14, s14, s15
	s_bfe_i32 s15, s14, 0x80000
	s_bfe_u32 s15, s15, 0x3000c
	s_add_i32 s15, s14, s15
	s_bfe_i32 s25, s15, 0x80000
	s_and_b32 s15, s15, 0xf8
	s_sub_i32 s14, s14, s15
	s_lshl_b32 s24, s24, 3
	s_sext_i32_i16 s25, s25
	s_sext_i32_i8 s14, s14
	s_add_i32 s46, s24, s14
	s_ashr_i32 s28, s25, 3

; #define PG8_LAS __attribute__((address_space(3)))
; #define PG8_WAIT_V(n) asm volatile("s_waitcnt vmcnt(" #n ")" ::: "memory")
; template <class Epi, class Sched, bool ALIGN_EPI = false, bool SP2 = false>
; __device__ __forceinline__ void gemm_phase(PG8_LAS unsigned char* lds, const Gemm g, const Sched& S, const Epi& E, const int wv) {
;     const int wid = wv, lane = hw_lane(), tid = wid * 64 + lane, wr = wid >> 2, wc = wid & 3, fr = lane & 15, fq = lane >> 4;
;     const int K = g.K, nt = K / BK;
;     unsigned voffA[2], voffB[2];
; #pragma unroll
;     for (int i = 0; i < 2; ++i) { int R, C; stage_rc(tid * 16 + i * 8192, R, C); const int Rb = Epi::PERM ? ((R & ~31) + perm32(R & 31)) : R;
;         voffA[i] = (unsigned)(R * K + C) * 2u; voffB[i] = (unsigned)(Rb * K + C) * 2u; }
;     const size_t kstep = (size_t)(BK * 2);
;     const size_t hstep = (size_t)HALF * K * 2;
;     const size_t tstep = 2 * hstep;
;     const unsigned ldsw = (unsigned)wid * 1024u;
;     const int aoff = lds_byte(wr * 64 + fr, fq * 8), boff = lds_byte(wc * 32 + fr, fq * 8);
;     ...
;     Unit cur, nxt; int ui = 0;
;     if (!S.next(0, cur)) return;
;     f32x4 acc[2][2][4][2];
; #pragma unroll
;     for (int a = 0; a < 2; ++a)
; #pragma unroll
;         for (int b = 0; b < 2; ++b)
; #pragma unroll
;             for (int m = 0; m < 4; ++m)
; #pragma unroll
;                 for (int n = 0; n < 2; ++n) acc[a][b][m][n] = (f32x4){0.f, 0.f, 0.f, 0.f};
;     bf16x8 At[4][2], B0[2][2], B1[2][2];
;     const char* cA = (const char*)g.A + (size_t)cur.pm * tstep; const char* cB = (const char*)g.Bt + (size_t)cur.pn * tstep;
;     S.a_ready(cur);
;     if constexpr (SP2) {
;         PG8_STAGE(PG8_SB(0, 0), cB, voffB); PG8_STAGE(PG8_SB(0, 1), cB + hstep, voffB); PG8_STAGE(PG8_SA(0, 0), cA, voffA); PG8_STAGE(PG8_SA(0, 1), cA + hstep, voffA);
;         if (wr == 1) PG8_BAR;
;         PG8_WAIT_V(2); PG8_BAR;
;         PG8_STAGE(PG8_SB(1, 0), cB + kstep, voffB); PG8_STAGE(PG8_SA(1, 0), cA + kstep, voffA); PG8_STAGE(PG8_SB(1, 1), cB + hstep + kstep, voffB);
;         PG8_WAIT_V(6); PG8_BAR;
;     } else {
; __global__ void __launch_bounds__(NTHR, 2) hybrid_fwd(Args args) {
;     ...
;     { pg8::Gemm g{X1B, Wxq, T, 512, 1024}; pg8::StaticOrder S; S.init(T, 512, G, blk);
;       epi::ScaleRow E{QX, 512, SSQ1};
;       pg8::gemm_phase<epi::ScaleRow, pg8::StaticOrder, PG8_ALIGN, PG8_SP2>(ldsl, g, S, E, wave); }
.LBB0_601:
	s_mov_b64 s[12:13], s[18:19]
	s_waitcnt lgkmcnt(0)
	s_waitcnt lgkmcnt(0)
	s_waitcnt lgkmcnt(0)
	s_waitcnt lgkmcnt(0)
	s_waitcnt lgkmcnt(0)
	s_waitcnt lgkmcnt(0)
	s_waitcnt lgkmcnt(0)
	s_waitcnt lgkmcnt(0)
	s_waitcnt lgkmcnt(0)
	s_waitcnt lgkmcnt(0)
	s_waitcnt lgkmcnt(0)
	s_waitcnt lgkmcnt(0)
	s_waitcnt lgkmcnt(0)
	s_waitcnt lgkmcnt(0)
	s_waitcnt lgkmcnt(0)
	s_waitcnt lgkmcnt(0)
	s_waitcnt lgkmcnt(0)
	s_waitcnt lgkmcnt(0)
	s_waitcnt lgkmcnt(0)
	s_waitcnt lgkmcnt(0)
	s_mov_b64 s[24:25], s[16:17]
	v_mov_b32_e32 v10, v212
	s_cmpk_gt_i32 s2, 0xff
	s_waitcnt lgkmcnt(0)
	s_cbranch_scc1 .LBB0_621
	v_lshl_add_u32 v0, v10, 4, s64
	v_add_u32_e32 v1, 0x2000, v0
	v_ashrrev_i32_e32 v2, 31, v1
	v_lshrrev_b32_e32 v2, 22, v2
	v_add_u32_e32 v2, v1, v2
	v_ashrrev_i32_e32 v8, 10, v2
	v_mul_i32_i24_e32 v2, 0x400, v8
	v_sub_u32_e32 v1, v1, v2
	v_lshrrev_b32_e32 v2, 4, v1
	v_bitop3_b32 v1, v2, v1, 32 bitop3:0x6c
	v_ashrrev_i32_e32 v2, 31, v1
	v_lshrrev_b32_e32 v2, 26, v2
	v_add_u32_e32 v2, v1, v2
	v_ashrrev_i32_e32 v9, 6, v2
	v_lshlrev_b32_e32 v3, 3, v8
	v_and_b32_e32 v2, 0xffc0, v2
	v_and_b32_e32 v3, -16, v3
	v_sub_u32_e32 v1, v1, v2
	v_add_u32_e32 v3, v9, v3
	v_lshrrev_b16_e32 v2, 7, v1
	v_and_b32_e32 v4, 3, v9
	s_mov_b32 s14, 0x1fffe0
	v_lshrrev_b32_e32 v5, 2, v3
	v_lshlrev_b32_e32 v6, 1, v3
	v_and_b32_e32 v2, 1, v2
	v_and_or_b32 v4, v3, s14, v4
	v_and_b32_e32 v5, 4, v5
	v_and_b32_e32 v6, 24, v6
	v_add_u16_e32 v1, v1, v2
	v_mov_b32_e32 v2, 1
	v_or3_b32 v4, v4, v5, v6
	v_lshlrev_b32_e32 v5, 5, v8
	v_ashrrev_i16_sdwa v1, v2, sext(v1) dst_sel:DWORD dst_unused:UNUSED_PAD src0_sel:DWORD src1_sel:BYTE_0
	v_and_b32_e32 v5, 32, v5
	v_bfe_i32 v11, v1, 0, 16
	v_add_lshl_u32 v1, v5, v11, 1
	v_lshl_add_u32 v140, v4, 11, v1
	v_lshl_add_u32 v142, v3, 11, v1
	v_ashrrev_i32_e32 v1, 31, v0
	v_lshrrev_b32_e32 v1, 22, v1
	v_add_u32_e32 v1, v0, v1
	v_ashrrev_i32_e32 v12, 10, v1
	v_mul_i32_i24_e32 v1, 0x400, v12
	v_sub_u32_e32 v0, v0, v1
	v_lshrrev_b32_e32 v1, 4, v0
	v_bitop3_b32 v0, v1, v0, 32 bitop3:0x6c
	v_ashrrev_i32_e32 v1, 31, v0
	s_add_u32 s46, s12, 0xd00000
	v_lshrrev_b32_e32 v1, 26, v1
	s_addc_u32 s47, s13, 0
	v_add_u32_e32 v1, v0, v1
	v_lshlrev_b32_e32 v3, 3, v12
	s_add_u32 s48, s12, 0x3c00000
	v_ashrrev_i32_e32 v13, 6, v1
	v_and_b32_e32 v3, -16, v3
	s_addc_u32 s49, s13, 0
	v_add_u32_e32 v3, v13, v3
	v_and_b32_e32 v4, 3, v13
	s_lshl_b32 s25, s68, 5
	v_and_or_b32 v4, v3, s14, v4
	s_mul_i32 s24, s68, 33
	s_and_b64 s[14:15], s[94:95], exec
	s_cselect_b32 s14, s24, s25
	s_add_i32 s14, s14, s67
	s_ashr_i32 s15, s14, 31
	s_lshr_b32 s15, s15, 28
	s_add_i32 s15, s14, s15
	s_ashr_i32 s24, s15, 4
	s_and_b32 s15, s15, 0xfff0
	s_sub_i32 s14, s14, s15
	s_bfe_i32 s15, s14, 0x80000
	s_bfe_u32 s15, s15, 0x3000c
	s_add_i32 s15, s14, s15
	s_bfe_i32 s25, s15, 0x80000
	s_and_b32 s15, s15, 0xf8
	s_sub_i32 s14, s14, s15
	s_lshl_b32 s24, s24, 3
	s_sext_i32_i16 s25, s25
	s_sext_i32_i8 s14, s14
	v_lshrrev_b32_e32 v5, 2, v3
	v_lshlrev_b32_e32 v6, 1, v3
	v_and_b32_e32 v1, 0xc0, v1
	s_lshr_b32 s28, s25, 3
	s_add_i32 s38, s24, s14
	v_and_b32_e32 v5, 4, v5
	v_and_b32_e32 v6, 24, v6
	v_sub_u32_e32 v0, v0, v1
	s_ashr_i32 s39, s38, 31
	s_bfe_i64 s[24:25], s[28:29], 0x100000
	v_or3_b32 v4, v4, v5, v6
	v_lshlrev_b32_e32 v5, 5, v12
	v_ashrrev_i16_sdwa v0, v2, sext(v0) dst_sel:DWORD dst_unused:UNUSED_PAD src0_sel:DWORD src1_sel:BYTE_0
	s_lshl_b64 s[14:15], s[38:39], 19
	s_lshl_b64 s[24:25], s[24:25], 19
	v_and_b32_e32 v5, 32, v5
	v_bfe_i32 v14, v0, 0, 16
	s_add_u32 s42, s46, s24
	v_add_lshl_u32 v0, v5, v14, 1
	s_addc_u32 s43, s47, s25
	s_add_i32 s39, s64, 0
	v_lshl_add_u32 v144, v4, 11, v0
	s_add_i32 m0, s39, 0x10000
	v_lshl_add_u32 v146, v3, 11, v0
	global_load_lds_dwordx4 v144, s[42:43]
	s_add_i32 m0, s39, 0x12000
	s_add_u32 s24, s42, 0x40000
	global_load_lds_dwordx4 v140, s[42:43]
	s_addc_u32 s25, s43, 0
	s_add_i32 m0, s39, 0x14000
	v_mov_b32_e32 v145, 0
	global_load_lds_dwordx4 v144, s[24:25]
	s_add_i32 m0, s39, 0x16000
	s_add_u32 s40, s48, s14
	s_addc_u32 s41, s49, s15
	s_add_i32 s50, s39, 0x2000
	global_load_lds_dwordx4 v140, s[24:25]
	s_mov_b32 m0, s39
	s_add_u32 s14, s40, 0x40000
	global_load_lds_dwordx4 v146, s[40:41]
	s_mov_b32 m0, s50
	s_addc_u32 s15, s41, 0
	s_add_i32 s51, s39, 0x4000
	global_load_lds_dwordx4 v142, s[40:41]
	s_mov_b32 m0, s51
	s_add_i32 s52, s39, 0x6000
	global_load_lds_dwordx4 v146, s[14:15]
	s_mov_b32 m0, s52
	v_mov_b32_e32 v141, v145
	global_load_lds_dwordx4 v142, s[14:15]
	v_mov_b32_e32 v147, v145
	v_mov_b32_e32 v143, v145
	v_lshl_add_u64 v[6:7], s[42:43], 0, v[144:145]
	v_lshl_add_u64 v[4:5], s[42:43], 0, v[140:141]
	v_lshl_add_u64 v[2:3], s[40:41], 0, v[146:147]
	s_and_b64 vcc, exec, s[6:7]
	v_lshl_add_u64 v[0:1], s[40:41], 0, v[142:143]
	s_cbranch_vccnz .LBB0_604
	s_barrier

; __device__ __forceinline__ int hw_lane() { int l = (int)__builtin_amdgcn_mbcnt_hi(~0u, __builtin_amdgcn_mbcnt_lo(~0u, 0u)); asm volatile("" : "+v"(l)); return l; }
; __device__ __forceinline__ gptr_t opq_ptr(const void* p) { gptr_t g = (gptr_t)p; asm volatile("" : "+s"(g)); return g; }
; __global__ void __launch_bounds__(NTHR, 2) hybrid_fwd(Args args) {
;     ...
;     for (int rep_ = 0; rep_ < REP_P5B; ++rep_) {
;     DECL_PTRS
;     (void)x; (void)mem; (void)out; (void)CC;
;     if (use_xcd) { if (wave == 0 && hw_lane() == 0) { while (__hip_atomic_load((unsigned*)opq_ptr(args.ws) + 64 * 10, __ATOMIC_RELAXED, __HIP_MEMORY_SCOPE_AGENT) < (unsigned)((TM / 256) * 4)) __builtin_amdgcn_s_sleep(2);
;           __builtin_amdgcn_fence(__ATOMIC_ACQUIRE, "agent"); asm volatile("s_waitcnt vmcnt(0)" ::: "memory"); }
;       __syncthreads(); }
;     { const int lane = hw_lane(); const int upb = ((T / 256) * 4 + G - 1) / G; for (int i = 0; i < upb; ++i) { const int un = hb * upb + i; if (un >= (T / 256) * 4) break; xattn_unit(un >> 2, un & 3, QX, KX, VXT, OX, wave, lane, ldsl); } }
.LBB0_642:
	s_mov_b64 s[26:27], s[18:19]
	s_mov_b32 s13, s20
	s_and_b32 s14, s13, 7
	s_mov_b32 s24, s2
	s_cmp_lg_u32 s14, 0
	s_cbranch_scc1 .LBB0_644
	s_ashr_i32 s15, s24, 31
	s_lshr_b32 s15, s15, 29
	s_add_i32 s15, s24, s15
	s_ashr_i32 s25, s15, 3
	s_and_b32 s15, s15, -8
	s_ashr_i32 s13, s13, 3
	s_sub_i32 s15, s24, s15
	s_mul_i32 s13, s15, s13
	s_add_i32 s24, s13, s25
.LBB0_644:
	s_waitcnt lgkmcnt(0)
	s_waitcnt lgkmcnt(0)
	s_waitcnt lgkmcnt(0)
	s_waitcnt lgkmcnt(0)
	s_waitcnt lgkmcnt(0)
	s_mov_b32 s28, 6
	s_waitcnt lgkmcnt(0)
	s_ashr_i32 s29, s28, 31
	s_waitcnt lgkmcnt(0)
	s_waitcnt lgkmcnt(0)
	s_waitcnt lgkmcnt(0)
	s_waitcnt lgkmcnt(0)
	s_waitcnt lgkmcnt(0)
	s_waitcnt lgkmcnt(0)
	s_waitcnt lgkmcnt(0)
	s_waitcnt lgkmcnt(0)
	s_waitcnt lgkmcnt(0)
	s_waitcnt lgkmcnt(0)
	s_waitcnt lgkmcnt(0)
	s_waitcnt lgkmcnt(0)
	s_waitcnt lgkmcnt(0)
	s_and_b64 vcc, exec, s[8:9]
	s_waitcnt lgkmcnt(0)
	s_cbranch_vccnz .LBB0_654
	s_and_b64 vcc, exec, s[4:5]
	s_cbranch_vccnz .LBB0_653
	v_mov_b32_e32 v0, v212
	s_nop 0
	v_cmp_eq_u32_e32 vcc, 0, v0
	s_and_saveexec_b64 s[12:13], vcc
	s_cbranch_execz .LBB0_652
	v_mov_b32_e32 v0, 0
	s_branch .LBB0_649

; __global__ void __launch_bounds__(NTHR, 2) hybrid_fwd(Args args) {
;     ...
;     { pg8::Gemm g{OX, Wxo, T, 1024, 512}; pg8::StaticOrder S; S.init(T, 1024, G, blk);
;       epi::Resid<true> E{X1B, X2B, SSQ2};
;       pg8::gemm_phase<epi::Resid<true>, pg8::StaticOrder, PG8_ALIGN, PG8_SP2>(ldsl, g, S, E, wave); }
.LBB0_682:
	s_mov_b64 s[12:13], s[18:19]
	s_waitcnt lgkmcnt(0)
	s_waitcnt lgkmcnt(0)
	s_waitcnt lgkmcnt(0)
	s_waitcnt lgkmcnt(0)
	s_waitcnt lgkmcnt(0)
	s_waitcnt lgkmcnt(0)
	s_waitcnt lgkmcnt(0)
	s_waitcnt lgkmcnt(0)
	s_waitcnt lgkmcnt(0)
	s_waitcnt lgkmcnt(0)
	s_waitcnt lgkmcnt(0)
	s_waitcnt lgkmcnt(0)
	s_waitcnt lgkmcnt(0)
	s_waitcnt lgkmcnt(0)
	s_waitcnt lgkmcnt(0)
	s_waitcnt lgkmcnt(0)
	s_waitcnt lgkmcnt(0)
	s_waitcnt lgkmcnt(0)
	s_waitcnt lgkmcnt(0)
	s_mov_b64 s[24:25], s[16:17]
	v_mov_b32_e32 v8, v212
	s_and_b64 vcc, exec, s[10:11]
	s_waitcnt lgkmcnt(0)
	s_cbranch_vccz .LBB0_703
	s_and_b64 vcc, exec, s[10:11]
	s_cbranch_vccz .LBB0_704

; #define PG8_LAS __attribute__((address_space(3)))
; #define PG8_WAIT_V(n) asm volatile("s_waitcnt vmcnt(" #n ")" ::: "memory")
; template <class Epi, class Sched, bool ALIGN_EPI = false, bool SP2 = false>
; __device__ __forceinline__ void gemm_phase(PG8_LAS unsigned char* lds, const Gemm g, const Sched& S, const Epi& E, const int wv) {
;     const int wid = wv, lane = hw_lane(), tid = wid * 64 + lane, wr = wid >> 2, wc = wid & 3, fr = lane & 15, fq = lane >> 4;
;     const int K = g.K, nt = K / BK;
;     unsigned voffA[2], voffB[2];
; #pragma unroll
;     for (int i = 0; i < 2; ++i) { int R, C; stage_rc(tid * 16 + i * 8192, R, C); const int Rb = Epi::PERM ? ((R & ~31) + perm32(R & 31)) : R;
;         voffA[i] = (unsigned)(R * K + C) * 2u; voffB[i] = (unsigned)(Rb * K + C) * 2u; }
;     const size_t kstep = (size_t)(BK * 2);
;     const size_t hstep = (size_t)HALF * K * 2;
;     const size_t tstep = 2 * hstep;
;     const unsigned ldsw = (unsigned)wid * 1024u;
;     const int aoff = lds_byte(wr * 64 + fr, fq * 8), boff = lds_byte(wc * 32 + fr, fq * 8);
;     ...
;     Unit cur, nxt; int ui = 0;
;     if (!S.next(0, cur)) return;
;     f32x4 acc[2][2][4][2];
; #pragma unroll
;     for (int a = 0; a < 2; ++a)
; #pragma unroll
;         for (int b = 0; b < 2; ++b)
; #pragma unroll
;             for (int m = 0; m < 4; ++m)
; #pragma unroll
;                 for (int n = 0; n < 2; ++n) acc[a][b][m][n] = (f32x4){0.f, 0.f, 0.f, 0.f};
;     bf16x8 At[4][2], B0[2][2], B1[2][2];
;     const char* cA = (const char*)g.A + (size_t)cur.pm * tstep; const char* cB = (const char*)g.Bt + (size_t)cur.pn * tstep;
;     S.a_ready(cur);
;     if constexpr (SP2) {
;         PG8_STAGE(PG8_SB(0, 0), cB, voffB); PG8_STAGE(PG8_SB(0, 1), cB + hstep, voffB); PG8_STAGE(PG8_SA(0, 0), cA, voffA); PG8_STAGE(PG8_SA(0, 1), cA + hstep, voffA);
;         if (wr == 1) PG8_BAR;
;         PG8_WAIT_V(2); PG8_BAR;
;         PG8_STAGE(PG8_SB(1, 0), cB + kstep, voffB); PG8_STAGE(PG8_SA(1, 0), cA + kstep, voffA); PG8_STAGE(PG8_SB(1, 1), cB + hstep + kstep, voffB);
;         PG8_WAIT_V(6); PG8_BAR;
;     } else {
; __global__ void __launch_bounds__(NTHR, 2) hybrid_fwd(Args args) {
;     ...
;     { pg8::Gemm g{X2B, Wffi, T, 2 * DFF, 1024}; pg8::StaticOrder S; S.init(T, 2 * DFF, G, blk);
;       epi::SwiGLU E{ACT, SSQ2};
;       pg8::gemm_phase<epi::SwiGLU, pg8::StaticOrder, PG8_ALIGN, PG8_SP2>(ldsl, g, S, E, wave); }
.LBB0_741:
	s_mov_b64 s[12:13], s[18:19]
	s_waitcnt lgkmcnt(0)
	s_waitcnt lgkmcnt(0)
	s_waitcnt lgkmcnt(0)
	s_waitcnt lgkmcnt(0)
	s_waitcnt lgkmcnt(0)
	s_waitcnt lgkmcnt(0)
	s_waitcnt lgkmcnt(0)
	s_waitcnt lgkmcnt(0)
	s_waitcnt lgkmcnt(0)
	s_waitcnt lgkmcnt(0)
	s_waitcnt lgkmcnt(0)
	s_waitcnt lgkmcnt(0)
	s_waitcnt lgkmcnt(0)
	s_waitcnt lgkmcnt(0)
	s_waitcnt lgkmcnt(0)
	s_waitcnt lgkmcnt(0)
	s_waitcnt lgkmcnt(0)
	s_waitcnt lgkmcnt(0)
	s_waitcnt lgkmcnt(0)
	s_waitcnt lgkmcnt(0)
	s_mov_b64 s[24:25], s[16:17]
	v_mov_b32_e32 v10, v212
	s_cmpk_gt_i32 s2, 0xaff
	s_waitcnt lgkmcnt(0)
	s_cbranch_scc1 .LBB0_757
	v_lshl_add_u32 v0, v10, 4, s64
	v_add_u32_e32 v1, 0x2000, v0
	v_ashrrev_i32_e32 v2, 31, v1
	v_lshrrev_b32_e32 v2, 22, v2
	v_add_u32_e32 v2, v1, v2
	v_ashrrev_i32_e32 v8, 10, v2
	v_mul_i32_i24_e32 v2, 0x400, v8
	v_sub_u32_e32 v1, v1, v2
	v_lshrrev_b32_e32 v2, 4, v1
	v_bitop3_b32 v1, v2, v1, 32 bitop3:0x6c
	v_ashrrev_i32_e32 v2, 31, v1
	v_lshrrev_b32_e32 v2, 26, v2
	v_add_u32_e32 v2, v1, v2
	v_ashrrev_i32_e32 v9, 6, v2
	v_lshlrev_b32_e32 v3, 3, v8
	v_and_b32_e32 v2, 0xffc0, v2
	v_and_b32_e32 v3, -16, v3
	v_sub_u32_e32 v1, v1, v2
	v_add_u32_e32 v3, v9, v3
	v_lshrrev_b16_e32 v2, 7, v1
	v_and_b32_e32 v4, 3, v9
	s_mov_b32 s14, 0x1fffe0
	v_lshrrev_b32_e32 v5, 2, v3
	v_lshlrev_b32_e32 v6, 1, v3
	v_and_b32_e32 v2, 1, v2
	v_and_or_b32 v4, v3, s14, v4
	v_and_b32_e32 v5, 4, v5
	v_and_b32_e32 v6, 24, v6
	v_add_u16_e32 v1, v1, v2
	v_mov_b32_e32 v2, 1
	v_or3_b32 v4, v4, v5, v6
	v_lshlrev_b32_e32 v5, 5, v8
	v_ashrrev_i16_sdwa v1, v2, sext(v1) dst_sel:DWORD dst_unused:UNUSED_PAD src0_sel:DWORD src1_sel:BYTE_0
	v_and_b32_e32 v5, 32, v5
	v_bfe_i32 v11, v1, 0, 16
	v_add_lshl_u32 v1, v5, v11, 1
	v_lshl_add_u32 v140, v4, 11, v1
	v_lshl_add_u32 v142, v3, 11, v1
	v_ashrrev_i32_e32 v1, 31, v0
	v_lshrrev_b32_e32 v1, 22, v1
	v_add_u32_e32 v1, v0, v1
	v_ashrrev_i32_e32 v12, 10, v1
	v_mul_i32_i24_e32 v1, 0x400, v12
	v_sub_u32_e32 v0, v0, v1
	v_lshrrev_b32_e32 v1, 4, v0
	v_bitop3_b32 v0, v1, v0, 32 bitop3:0x6c
	v_ashrrev_i32_e32 v1, 31, v0
	s_add_u32 s46, s12, 0x1100000
	v_lshrrev_b32_e32 v1, 26, v1
	s_addc_u32 s47, s13, 0
	v_add_u32_e32 v1, v0, v1
	v_lshlrev_b32_e32 v3, 3, v12
	s_add_u32 s48, s12, 0x3c00000
	v_ashrrev_i32_e32 v13, 6, v1
	v_and_b32_e32 v3, -16, v3
	s_addc_u32 s49, s13, 0
	v_add_u32_e32 v3, v13, v3
	v_and_b32_e32 v4, 3, v13
	v_and_or_b32 v4, v3, s14, v4
	s_movk_i32 s50, 0x161
	s_and_b64 s[14:15], s[94:95], exec
	s_cselect_b32 s14, s50, 0x160
	s_mul_i32 s14, s68, s14
	s_add_i32 s14, s14, s67
	s_mul_hi_i32 s15, s14, 0x2e8ba2e9
	s_lshr_b32 s24, s15, 31
	s_ashr_i32 s15, s15, 5
	s_add_i32 s15, s15, s24
	s_lshl_b32 s24, s15, 3
	s_mulk_i32 s15, 0xb0
	s_sub_i32 s14, s14, s15
	s_bfe_u32 s15, s14, 0x3001c
	s_add_i32 s15, s14, s15
	s_sext_i32_i16 s25, s15
	s_and_b32 s15, s15, 0xfff8
	s_sub_i32 s14, s14, s15
	s_sext_i32_i16 s14, s14
	v_lshrrev_b32_e32 v5, 2, v3
	v_lshlrev_b32_e32 v6, 1, v3
	v_and_b32_e32 v1, 0xc0, v1
	s_lshr_b32 s28, s25, 3
	s_add_i32 s38, s24, s14
	v_and_b32_e32 v5, 4, v5
	v_and_b32_e32 v6, 24, v6
	v_sub_u32_e32 v0, v0, v1
	s_ashr_i32 s39, s38, 31
	s_bfe_i64 s[24:25], s[28:29], 0x100000
	v_or3_b32 v4, v4, v5, v6
	v_lshlrev_b32_e32 v5, 5, v12
	v_ashrrev_i16_sdwa v0, v2, sext(v0) dst_sel:DWORD dst_unused:UNUSED_PAD src0_sel:DWORD src1_sel:BYTE_0
	s_lshl_b64 s[14:15], s[38:39], 19
	s_lshl_b64 s[24:25], s[24:25], 19
	v_and_b32_e32 v5, 32, v5
	v_bfe_i32 v14, v0, 0, 16
	s_add_u32 s42, s46, s24
	v_add_lshl_u32 v0, v5, v14, 1
	s_addc_u32 s43, s47, s25
	s_add_i32 s39, s64, 0
	v_lshl_add_u32 v144, v4, 11, v0
	s_add_i32 m0, s39, 0x10000
	v_lshl_add_u32 v146, v3, 11, v0
	global_load_lds_dwordx4 v144, s[42:43]
	s_add_i32 m0, s39, 0x12000
	s_add_u32 s24, s42, 0x40000
	global_load_lds_dwordx4 v140, s[42:43]
	s_addc_u32 s25, s43, 0
	s_add_i32 m0, s39, 0x14000
	v_mov_b32_e32 v145, 0
	global_load_lds_dwordx4 v144, s[24:25]
	s_add_i32 m0, s39, 0x16000
	s_add_u32 s40, s48, s14
	s_addc_u32 s41, s49, s15
	s_add_i32 s51, s39, 0x2000
	global_load_lds_dwordx4 v140, s[24:25]
	s_mov_b32 m0, s39
	s_add_u32 s14, s40, 0x40000
	global_load_lds_dwordx4 v146, s[40:41]
	s_mov_b32 m0, s51
	s_addc_u32 s15, s41, 0
	s_add_i32 s52, s39, 0x4000
	global_load_lds_dwordx4 v142, s[40:41]
	s_mov_b32 m0, s52
	s_add_i32 s53, s39, 0x6000
	global_load_lds_dwordx4 v146, s[14:15]
	s_mov_b32 m0, s53
	v_mov_b32_e32 v141, v145
	global_load_lds_dwordx4 v142, s[14:15]
	v_mov_b32_e32 v147, v145
	v_mov_b32_e32 v143, v145
	v_lshl_add_u64 v[6:7], s[42:43], 0, v[144:145]
	v_lshl_add_u64 v[4:5], s[42:43], 0, v[140:141]
	v_lshl_add_u64 v[2:3], s[40:41], 0, v[146:147]
	s_and_b64 vcc, exec, s[6:7]
	v_lshl_add_u64 v[0:1], s[40:41], 0, v[142:143]
	s_cbranch_vccnz .LBB0_744
	s_barrier

; __global__ void __launch_bounds__(NTHR, 2) hybrid_fwd(Args args) {
;     ...
;     { pg8::Gemm g{ACT, Wffo, T, 1024, DFF}; pg8::StaticOrder S; S.init(T, 1024, G, blk);
;       epi::Resid<true> E{X2B, X2B, SSQ3};
;       pg8::gemm_phase<epi::Resid<true>, pg8::StaticOrder, PG8_ALIGN, PG8_SP2>(ldsl, g, S, E, wave); }
.LBB0_778:
	s_mov_b64 s[12:13], s[18:19]
	s_waitcnt lgkmcnt(0)
	s_waitcnt lgkmcnt(0)
	s_waitcnt lgkmcnt(0)
	s_waitcnt lgkmcnt(0)
	s_waitcnt lgkmcnt(0)
	s_waitcnt lgkmcnt(0)
	s_waitcnt lgkmcnt(0)
	s_waitcnt lgkmcnt(0)
	s_waitcnt lgkmcnt(0)
	s_waitcnt lgkmcnt(0)
	s_waitcnt lgkmcnt(0)
	s_waitcnt lgkmcnt(0)
	s_waitcnt lgkmcnt(0)
	s_waitcnt lgkmcnt(0)
	s_waitcnt lgkmcnt(0)
	s_waitcnt lgkmcnt(0)
	s_waitcnt lgkmcnt(0)
	s_waitcnt lgkmcnt(0)
	s_waitcnt lgkmcnt(0)
	v_mov_b32_e32 v8, v212
	s_and_b64 vcc, exec, s[10:11]
	s_waitcnt lgkmcnt(0)
	s_cbranch_vccz .LBB0_790
	s_and_b64 vcc, exec, s[10:11]
	s_cbranch_vccz .LBB0_791

; __device__ __forceinline__ int hw_lane() { int l = (int)__builtin_amdgcn_mbcnt_hi(~0u, __builtin_amdgcn_mbcnt_lo(~0u, 0u)); asm volatile("" : "+v"(l)); return l; }
; __global__ void __launch_bounds__(NTHR, 2) hybrid_fwd(Args args) {
;     ...
;     DECL_PTRS
;     (void)x; (void)mem; (void)out; (void)CC;
;     { const int lane = hw_lane();
;     const int rpb = (T + G - 1) / G, rpw = (rpb + NWAVES - 1) / NWAVES;
;     const int row_b = hb * rpb + wave * rpw; int nrows = rpb - wave * rpw; if (nrows > rpw) nrows = rpw; if (row_b + nrows > T) nrows = T - row_b;
;     f32x4 gv[4];
; #pragma unroll
;     for (int j = 0; j < 4; ++j) gv[j] = ((const f32x4*)norm_final_g + lane)[64 * j];
;     f32x4 pa_n = {0.f, 0.f, 0.f, 0.f}; unsigned long long q_n[4] = {0ull, 0ull, 0ull, 0ull};
;     if (nrows > 0) { pa_n = *(const f32x4*)(SSQ3 + (size_t)row_b * 16 + 4 * (lane & 3));
; #pragma unroll
;         for (int j = 0; j < 4; ++j) q_n[j] = ((const unsigned long long*)(X2B + (size_t)row_b * DM) + lane)[64 * j]; }
.LBB0_840:
	s_waitcnt lgkmcnt(0)
	s_and_b32 s3, s20, 7
	s_cmp_lg_u32 s3, 0
	s_cbranch_scc1 .LBB0_842
	s_ashr_i32 s5, s2, 31
	s_lshr_b32 s5, s5, 29
	s_add_i32 s5, s2, s5
	s_ashr_i32 s7, s5, 3
	s_and_b32 s5, s5, -8
	s_ashr_i32 s3, s20, 3
	s_sub_i32 s2, s2, s5
	s_mul_i32 s2, s2, s3
	s_add_i32 s2, s2, s7
.LBB0_842:
	s_waitcnt lgkmcnt(0)
	s_waitcnt lgkmcnt(0)
	s_waitcnt lgkmcnt(0)
	s_waitcnt lgkmcnt(0)
	s_waitcnt lgkmcnt(0)
	s_waitcnt lgkmcnt(0)
	s_waitcnt lgkmcnt(0)
	s_waitcnt lgkmcnt(0)
	s_waitcnt lgkmcnt(0)
	s_waitcnt lgkmcnt(0)
	s_waitcnt lgkmcnt(0)
	s_waitcnt lgkmcnt(0)
	s_waitcnt lgkmcnt(0)
	s_waitcnt lgkmcnt(0)
	s_waitcnt lgkmcnt(0)
	s_waitcnt lgkmcnt(0)
	s_waitcnt lgkmcnt(0)
	s_waitcnt lgkmcnt(0)
	s_mov_b32 s8, 19
	s_waitcnt lgkmcnt(0)
	s_ashr_i32 s9, s8, 31
	s_mul_i32 s56, s56, s2
	s_lshl_b64 s[2:3], s[8:9], 3
	s_add_u32 s0, s0, s2
	v_readlane_b32 s2, v248, 5
	s_addc_u32 s1, s1, s3
	s_add_i32 s2, s2, s56
	s_add_i32 s3, s57, s2
	s_sub_i32 s4, 0x8000, s2
	s_cmp_gt_i32 s3, 0x8000
	s_cselect_b32 s7, s4, s57
	s_mov_b32 s6, 1
	s_load_dwordx2 s[0:1], s[0:1], 0x0
	s_cmp_lt_i32 s7, 1
	s_waitcnt lgkmcnt(0)
	s_cbranch_scc1 .LBB0_847
	v_ashrrev_i32_e32 v213, 31, v212
	v_lshlrev_b64 v[16:17], 4, v[212:213]
	v_lshl_add_u64 v[18:19], s[0:1], 0, v[16:17]
	s_add_u32 s0, s18, 0x3c00000
	s_addc_u32 s1, s19, 0
	s_add_u32 s4, s18, 0x3900000
	s_addc_u32 s5, s19, 0
	s_ashr_i32 s3, s2, 31
	s_lshl_b64 s[8:9], s[2:3], 6
	s_add_u32 s8, s4, s8
	v_lshlrev_b32_e32 v8, 4, v212
	s_addc_u32 s9, s5, s9
	v_and_b32_e32 v28, 48, v8
	global_load_dwordx4 v[0:3], v[18:19], off
	global_load_dwordx4 v[4:7], v[18:19], off offset:1024
	global_load_dwordx4 v[20:23], v28, s[8:9]
	s_lshl_b64 s[8:9], s[2:3], 11
	s_add_u32 s8, s0, s8
	s_addc_u32 s9, s1, s9
	v_lshlrev_b64 v[24:25], 3, v[212:213]
	v_lshl_add_u64 v[26:27], s[8:9], 0, v[24:25]
	global_load_dwordx2 v[44:45], v[26:27], off
	global_load_dwordx2 v[42:43], v[26:27], off offset:512
	global_load_dwordx2 v[40:41], v[26:27], off offset:1024
	global_load_dwordx2 v[30:31], v[26:27], off offset:1536
	global_load_dwordx4 v[8:11], v[18:19], off offset:2048
	global_load_dwordx4 v[12:15], v[18:19], off offset:3072
	v_mov_b32_e32 v29, 0
	v_lshl_add_u64 v[26:27], s[16:17], 0, v[16:17]
	v_mov_b32_e32 v46, 0x358637bd
	s_mov_b32 s3, 0xf800000
	v_mov_b32_e32 v47, 0x260
	v_lshl_add_u64 v[24:25], s[0:1], 0, v[24:25]
	v_lshl_add_u64 v[28:29], s[4:5], 0, v[28:29]
	s_waitcnt vmcnt(6)
	v_mov_b64_e32 v[16:17], v[20:21]
	s_waitcnt vmcnt(5)
	v_mov_b64_e32 v[32:33], v[44:45]
	s_waitcnt vmcnt(4)
	v_mov_b64_e32 v[34:35], v[42:43]
	s_waitcnt vmcnt(3)
	v_mov_b64_e32 v[36:37], v[40:41]
	s_waitcnt vmcnt(2)
	v_mov_b64_e32 v[38:39], v[30:31]
	v_mov_b64_e32 v[18:19], v[22:23]
	s_branch .LBB0_845
